# leading half takes its end-of-K-loop alignment barrier after issuing the first epilogue loads (latency runs under the wait for the trailing half)
# baseline (speedup 1.0000x reference)
.LBB0_143:
	v_add_u32_e32 v28, 0x10000, v83
	v_add_u32_e32 v80, 0x14000, v83
	ds_read_b128 v[16:19], v28
	ds_read_b128 v[20:23], v28 offset:1024
	ds_read_b128 v[24:27], v28 offset:2048
	ds_read_b128 v[28:31], v28 offset:3072
	ds_read_b128 v[152:155], v80
	ds_read_b128 v[160:163], v80 offset:1024
	ds_read_b128 v[168:171], v80 offset:2048
	ds_read_b128 v[176:179], v80 offset:3072
	s_add_i32 s7, s4, 0xfff84000
	s_cmp_eq_u32 s6, 28
	s_cselect_b32 s17, s0, s7
	s_cselect_b32 s16, s1, s5
	s_or_b32 s7, s17, 0x4000
	ds_read_b128 v[192:195], v245
	ds_read_b128 v[196:199], v245 offset:1024
	ds_read_b128 v[200:203], v245 offset:2048
	ds_read_b128 v[204:207], v245 offset:3072
	ds_read_b128 v[220:223], v245 offset:4096
	ds_read_b128 v[224:227], v245 offset:5120
	ds_read_b128 v[228:231], v245 offset:6144
	ds_read_b128 v[246:249], v245 offset:7168
	s_mov_b32 m0, s79
	s_nop 0
	buffer_load_dwordx4 v242, s[24:27], s4 offen lds
	s_nop 0
	s_mov_b32 m0, s83
	s_nop 0
	buffer_load_dwordx4 v243, s[24:27], s4 offen lds
	s_waitcnt vmcnt(8)
	s_waitcnt lgkmcnt(0)
	s_barrier
	s_setprio 1
	s_waitcnt lgkmcnt(7)
	v_mfma_f32_16x16x32_bf16 v[180:183], v[16:19], v[192:195], v[180:183]
	v_mfma_f32_16x16x32_bf16 v[164:167], v[24:27], v[192:195], v[164:167]
	s_waitcnt lgkmcnt(5)
	v_mfma_f32_16x16x32_bf16 v[148:151], v[16:19], v[200:203], v[148:151]
	v_mfma_f32_16x16x32_bf16 v[140:143], v[24:27], v[200:203], v[140:143]
	s_waitcnt lgkmcnt(3)
	v_mfma_f32_16x16x32_bf16 v[132:135], v[16:19], v[220:223], v[132:135]
	v_mfma_f32_16x16x32_bf16 v[124:127], v[24:27], v[220:223], v[124:127]
	s_waitcnt lgkmcnt(1)
	v_mfma_f32_16x16x32_bf16 v[116:119], v[16:19], v[228:231], v[116:119]
	v_mfma_f32_16x16x32_bf16 v[108:111], v[24:27], v[228:231], v[108:111]
	v_mfma_f32_16x16x32_bf16 v[180:183], v[20:23], v[196:199], v[180:183]
	v_mfma_f32_16x16x32_bf16 v[164:167], v[28:31], v[196:199], v[164:167]
	v_mfma_f32_16x16x32_bf16 v[148:151], v[20:23], v[204:207], v[148:151]
	v_mfma_f32_16x16x32_bf16 v[140:143], v[28:31], v[204:207], v[140:143]
	v_mfma_f32_16x16x32_bf16 v[132:135], v[20:23], v[224:227], v[132:135]
	v_mfma_f32_16x16x32_bf16 v[124:127], v[28:31], v[224:227], v[124:127]
	s_waitcnt lgkmcnt(0)
	v_mfma_f32_16x16x32_bf16 v[116:119], v[20:23], v[246:249], v[116:119]
	v_mfma_f32_16x16x32_bf16 v[108:111], v[28:31], v[246:249], v[108:111]
	s_setprio 0
	s_setprio 1
	v_mfma_f32_16x16x32_bf16 v[172:175], v[152:155], v[192:195], v[172:175]
	v_mfma_f32_16x16x32_bf16 v[156:159], v[168:171], v[192:195], v[156:159]
	v_mfma_f32_16x16x32_bf16 v[144:147], v[152:155], v[200:203], v[144:147]
	v_mfma_f32_16x16x32_bf16 v[136:139], v[168:171], v[200:203], v[136:139]
	v_mfma_f32_16x16x32_bf16 v[128:131], v[152:155], v[220:223], v[128:131]
	v_mfma_f32_16x16x32_bf16 v[120:123], v[168:171], v[220:223], v[120:123]
	v_mfma_f32_16x16x32_bf16 v[112:115], v[152:155], v[228:231], v[112:115]
	v_mfma_f32_16x16x32_bf16 v[104:107], v[168:171], v[228:231], v[104:107]
	v_mfma_f32_16x16x32_bf16 v[172:175], v[160:163], v[196:199], v[172:175]
	v_mfma_f32_16x16x32_bf16 v[156:159], v[176:179], v[196:199], v[156:159]
	v_mfma_f32_16x16x32_bf16 v[144:147], v[160:163], v[204:207], v[144:147]
	v_mfma_f32_16x16x32_bf16 v[136:139], v[176:179], v[204:207], v[136:139]
	v_mfma_f32_16x16x32_bf16 v[128:131], v[160:163], v[224:227], v[128:131]
	v_mfma_f32_16x16x32_bf16 v[120:123], v[176:179], v[224:227], v[120:123]
	v_mfma_f32_16x16x32_bf16 v[112:115], v[160:163], v[246:249], v[112:115]
	v_mfma_f32_16x16x32_bf16 v[104:107], v[176:179], v[246:249], v[104:107]
	s_setprio 0
	s_barrier
	ds_read_b128 v[192:195], v245 offset:16384
	ds_read_b128 v[196:199], v245 offset:17408
	ds_read_b128 v[200:203], v245 offset:18432
	ds_read_b128 v[204:207], v245 offset:19456
	ds_read_b128 v[220:223], v245 offset:20480
	ds_read_b128 v[224:227], v245 offset:21504
	ds_read_b128 v[228:231], v245 offset:22528
	ds_read_b128 v[246:249], v245 offset:23552
	s_mov_b32 m0, s51
	s_nop 0
	buffer_load_dwordx4 v242, s[56:59], s16 offen lds
	s_add_i32 s18, s16, 0x80000
	s_mov_b32 m0, s52
	s_nop 0
	buffer_load_dwordx4 v243, s[56:59], s16 offen lds
	s_nop 0
	s_mov_b32 m0, s53
	s_nop 0
	buffer_load_dwordx4 v242, s[56:59], s18 offen lds
	s_nop 0
	s_mov_b32 m0, s55
	s_nop 0
	buffer_load_dwordx4 v243, s[56:59], s18 offen lds
	s_nop 0
	s_mov_b32 m0, s31
	s_nop 0
	buffer_load_dwordx4 v242, s[24:27], s17 offen lds
	s_nop 0
	s_mov_b32 m0, s68
	s_nop 0
	buffer_load_dwordx4 v243, s[24:27], s17 offen lds
	s_waitcnt vmcnt(8)
	s_waitcnt lgkmcnt(0)
	s_barrier
	s_setprio 1
	s_waitcnt lgkmcnt(7)
	v_mfma_f32_16x16x32_bf16 v[76:79], v[16:19], v[192:195], v[76:79]
	v_mfma_f32_16x16x32_bf16 v[68:71], v[24:27], v[192:195], v[68:71]
	s_waitcnt lgkmcnt(5)
	v_mfma_f32_16x16x32_bf16 v[60:63], v[16:19], v[200:203], v[60:63]
	v_mfma_f32_16x16x32_bf16 v[52:55], v[24:27], v[200:203], v[52:55]
	s_waitcnt lgkmcnt(3)
	v_mfma_f32_16x16x32_bf16 v[44:47], v[16:19], v[220:223], v[44:47]
	v_mfma_f32_16x16x32_bf16 v[36:39], v[24:27], v[220:223], v[36:39]
	s_waitcnt lgkmcnt(1)
	v_mfma_f32_16x16x32_bf16 v[12:15], v[16:19], v[228:231], v[12:15]
	v_mfma_f32_16x16x32_bf16 v[4:7], v[24:27], v[228:231], v[4:7]
	v_mfma_f32_16x16x32_bf16 v[76:79], v[20:23], v[196:199], v[76:79]
	v_mfma_f32_16x16x32_bf16 v[68:71], v[28:31], v[196:199], v[68:71]
	v_mfma_f32_16x16x32_bf16 v[60:63], v[20:23], v[204:207], v[60:63]
	v_mfma_f32_16x16x32_bf16 v[52:55], v[28:31], v[204:207], v[52:55]
	v_mfma_f32_16x16x32_bf16 v[44:47], v[20:23], v[224:227], v[44:47]
	v_mfma_f32_16x16x32_bf16 v[36:39], v[28:31], v[224:227], v[36:39]
	s_waitcnt lgkmcnt(0)
	v_mfma_f32_16x16x32_bf16 v[12:15], v[20:23], v[246:249], v[12:15]
	v_mfma_f32_16x16x32_bf16 v[4:7], v[28:31], v[246:249], v[4:7]
	s_setprio 0
	s_setprio 1
	v_mfma_f32_16x16x32_bf16 v[40:43], v[152:155], v[220:223], v[40:43]
	v_mfma_f32_16x16x32_bf16 v[32:35], v[168:171], v[220:223], v[32:35]
	v_mfma_f32_16x16x32_bf16 v[8:11], v[152:155], v[228:231], v[8:11]
	v_mfma_f32_16x16x32_bf16 v[0:3], v[168:171], v[228:231], v[0:3]
	v_mfma_f32_16x16x32_bf16 v[16:19], v[152:155], v[192:195], v[72:75]
	v_mfma_f32_16x16x32_bf16 v[20:23], v[168:171], v[192:195], v[64:67]
	v_mfma_f32_16x16x32_bf16 v[24:27], v[152:155], v[200:203], v[56:59]
	v_mfma_f32_16x16x32_bf16 v[28:31], v[168:171], v[200:203], v[48:51]
	v_mfma_f32_16x16x32_bf16 v[40:43], v[160:163], v[224:227], v[40:43]
	v_mfma_f32_16x16x32_bf16 v[32:35], v[176:179], v[224:227], v[32:35]
	v_mfma_f32_16x16x32_bf16 v[8:11], v[160:163], v[246:249], v[8:11]
	v_mfma_f32_16x16x32_bf16 v[0:3], v[176:179], v[246:249], v[0:3]
	v_mfma_f32_16x16x32_bf16 v[16:19], v[160:163], v[196:199], v[16:19]
	v_mfma_f32_16x16x32_bf16 v[20:23], v[176:179], v[196:199], v[20:23]
	v_mfma_f32_16x16x32_bf16 v[24:27], v[160:163], v[204:207], v[24:27]
	v_mfma_f32_16x16x32_bf16 v[28:31], v[176:179], v[204:207], v[28:31]
	s_setprio 0
	s_barrier
	v_add_u32_e32 v72, 0x18000, v83
	v_add_u32_e32 v80, 0x1c000, v83
	ds_read_b128 v[48:51], v72
	ds_read_b128 v[56:59], v72 offset:1024
	ds_read_b128 v[64:67], v72 offset:2048
	ds_read_b128 v[72:75], v72 offset:3072
	ds_read_b128 v[152:155], v80
	ds_read_b128 v[160:163], v80 offset:1024
	ds_read_b128 v[168:171], v80 offset:2048
	ds_read_b128 v[176:179], v80 offset:3072
	ds_read_b128 v[192:195], v245 offset:32768
	ds_read_b128 v[196:199], v245 offset:33792
	ds_read_b128 v[200:203], v245 offset:34816
	ds_read_b128 v[204:207], v245 offset:35840
	ds_read_b128 v[220:223], v245 offset:36864
	ds_read_b128 v[224:227], v245 offset:37888
	ds_read_b128 v[228:231], v245 offset:38912
	ds_read_b128 v[246:249], v245 offset:39936
	s_add_i32 s17, s17, 0x80000
	s_mov_b32 m0, s69
	s_nop 0
	buffer_load_dwordx4 v242, s[24:27], s17 offen lds
	s_nop 0
	s_mov_b32 m0, s70
	s_nop 0
	buffer_load_dwordx4 v243, s[24:27], s17 offen lds
	s_waitcnt vmcnt(8)
	s_waitcnt lgkmcnt(0)
	s_barrier
	s_setprio 1
	s_waitcnt lgkmcnt(7)
	v_mfma_f32_16x16x32_bf16 v[180:183], v[48:51], v[192:195], v[180:183]
	v_mfma_f32_16x16x32_bf16 v[164:167], v[64:67], v[192:195], v[164:167]
	s_waitcnt lgkmcnt(5)
	v_mfma_f32_16x16x32_bf16 v[148:151], v[48:51], v[200:203], v[148:151]
	v_mfma_f32_16x16x32_bf16 v[140:143], v[64:67], v[200:203], v[140:143]
	s_waitcnt lgkmcnt(3)
	v_mfma_f32_16x16x32_bf16 v[132:135], v[48:51], v[220:223], v[132:135]
	v_mfma_f32_16x16x32_bf16 v[124:127], v[64:67], v[220:223], v[124:127]
	s_waitcnt lgkmcnt(1)
	v_mfma_f32_16x16x32_bf16 v[116:119], v[48:51], v[228:231], v[116:119]
	v_mfma_f32_16x16x32_bf16 v[108:111], v[64:67], v[228:231], v[108:111]
	v_mfma_f32_16x16x32_bf16 v[180:183], v[56:59], v[196:199], v[180:183]
	v_mfma_f32_16x16x32_bf16 v[164:167], v[72:75], v[196:199], v[164:167]
	v_mfma_f32_16x16x32_bf16 v[148:151], v[56:59], v[204:207], v[148:151]
	v_mfma_f32_16x16x32_bf16 v[140:143], v[72:75], v[204:207], v[140:143]
	v_mfma_f32_16x16x32_bf16 v[132:135], v[56:59], v[224:227], v[132:135]
	v_mfma_f32_16x16x32_bf16 v[124:127], v[72:75], v[224:227], v[124:127]
	s_waitcnt lgkmcnt(0)
	v_mfma_f32_16x16x32_bf16 v[116:119], v[56:59], v[246:249], v[116:119]
	v_mfma_f32_16x16x32_bf16 v[108:111], v[72:75], v[246:249], v[108:111]
	s_setprio 0
	s_setprio 1
	v_mfma_f32_16x16x32_bf16 v[172:175], v[152:155], v[192:195], v[172:175]
	v_mfma_f32_16x16x32_bf16 v[156:159], v[168:171], v[192:195], v[156:159]
	v_mfma_f32_16x16x32_bf16 v[144:147], v[152:155], v[200:203], v[144:147]
	v_mfma_f32_16x16x32_bf16 v[136:139], v[168:171], v[200:203], v[136:139]
	v_mfma_f32_16x16x32_bf16 v[128:131], v[152:155], v[220:223], v[128:131]
	v_mfma_f32_16x16x32_bf16 v[120:123], v[168:171], v[220:223], v[120:123]
	v_mfma_f32_16x16x32_bf16 v[112:115], v[152:155], v[228:231], v[112:115]
	v_mfma_f32_16x16x32_bf16 v[104:107], v[168:171], v[228:231], v[104:107]
	v_mfma_f32_16x16x32_bf16 v[172:175], v[160:163], v[196:199], v[172:175]
	v_mfma_f32_16x16x32_bf16 v[156:159], v[176:179], v[196:199], v[156:159]
	v_mfma_f32_16x16x32_bf16 v[144:147], v[160:163], v[204:207], v[144:147]
	v_mfma_f32_16x16x32_bf16 v[136:139], v[176:179], v[204:207], v[136:139]
	v_mfma_f32_16x16x32_bf16 v[128:131], v[160:163], v[224:227], v[128:131]
	v_mfma_f32_16x16x32_bf16 v[120:123], v[176:179], v[224:227], v[120:123]
	v_mfma_f32_16x16x32_bf16 v[112:115], v[160:163], v[246:249], v[112:115]
	v_mfma_f32_16x16x32_bf16 v[104:107], v[176:179], v[246:249], v[104:107]
	s_setprio 0
	s_barrier
	ds_read_b128 v[192:195], v245 offset:49152
	ds_read_b128 v[196:199], v245 offset:50176
	ds_read_b128 v[200:203], v245 offset:51200
	ds_read_b128 v[204:207], v245 offset:52224
	ds_read_b128 v[220:223], v245 offset:53248
	ds_read_b128 v[224:227], v245 offset:54272
	ds_read_b128 v[228:231], v245 offset:55296
	ds_read_b128 v[246:249], v245 offset:56320
	s_or_b32 s17, s16, 0x4000
	s_mov_b32 m0, s73
	s_nop 0
	buffer_load_dwordx4 v242, s[56:59], s17 offen lds
	s_add_i32 s16, s16, 0x84000
	s_mov_b32 m0, s74
	s_nop 0
	buffer_load_dwordx4 v243, s[56:59], s17 offen lds
	s_nop 0
	s_mov_b32 m0, s77
	s_nop 0
	buffer_load_dwordx4 v242, s[56:59], s16 offen lds
	s_nop 0
	s_mov_b32 m0, s78
	s_nop 0
	buffer_load_dwordx4 v243, s[56:59], s16 offen lds
	s_nop 0
	s_mov_b32 m0, s75
	s_nop 0
	buffer_load_dwordx4 v242, s[24:27], s7 offen lds
	s_nop 0
	s_mov_b32 m0, s76
	s_nop 0
	buffer_load_dwordx4 v243, s[24:27], s7 offen lds
	s_waitcnt vmcnt(8)
	s_waitcnt lgkmcnt(0)
	s_barrier
	s_setprio 1
	s_waitcnt lgkmcnt(7)
	v_mfma_f32_16x16x32_bf16 v[76:79], v[48:51], v[192:195], v[76:79]
	v_mfma_f32_16x16x32_bf16 v[68:71], v[64:67], v[192:195], v[68:71]
	s_waitcnt lgkmcnt(5)
	v_mfma_f32_16x16x32_bf16 v[60:63], v[48:51], v[200:203], v[60:63]
	v_mfma_f32_16x16x32_bf16 v[52:55], v[64:67], v[200:203], v[52:55]
	s_waitcnt lgkmcnt(3)
	v_mfma_f32_16x16x32_bf16 v[44:47], v[48:51], v[220:223], v[44:47]
	v_mfma_f32_16x16x32_bf16 v[36:39], v[64:67], v[220:223], v[36:39]
	s_waitcnt lgkmcnt(1)
	v_mfma_f32_16x16x32_bf16 v[12:15], v[48:51], v[228:231], v[12:15]
	v_mfma_f32_16x16x32_bf16 v[4:7], v[64:67], v[228:231], v[4:7]
	v_mfma_f32_16x16x32_bf16 v[76:79], v[56:59], v[196:199], v[76:79]
	v_mfma_f32_16x16x32_bf16 v[68:71], v[72:75], v[196:199], v[68:71]
	v_mfma_f32_16x16x32_bf16 v[60:63], v[56:59], v[204:207], v[60:63]
	v_mfma_f32_16x16x32_bf16 v[52:55], v[72:75], v[204:207], v[52:55]
	v_mfma_f32_16x16x32_bf16 v[44:47], v[56:59], v[224:227], v[44:47]
	v_mfma_f32_16x16x32_bf16 v[36:39], v[72:75], v[224:227], v[36:39]
	s_waitcnt lgkmcnt(0)
	v_mfma_f32_16x16x32_bf16 v[12:15], v[56:59], v[246:249], v[12:15]
	v_mfma_f32_16x16x32_bf16 v[4:7], v[72:75], v[246:249], v[4:7]
	s_setprio 0
	s_setprio 1
	v_mfma_f32_16x16x32_bf16 v[16:19], v[152:155], v[192:195], v[16:19]
	v_mfma_f32_16x16x32_bf16 v[72:75], v[160:163], v[196:199], v[16:19]
	v_mfma_f32_16x16x32_bf16 v[16:19], v[168:171], v[192:195], v[20:23]
	v_mfma_f32_16x16x32_bf16 v[64:67], v[176:179], v[196:199], v[16:19]
	v_mfma_f32_16x16x32_bf16 v[16:19], v[152:155], v[200:203], v[24:27]
	v_mfma_f32_16x16x32_bf16 v[56:59], v[160:163], v[204:207], v[16:19]
	v_mfma_f32_16x16x32_bf16 v[16:19], v[168:171], v[200:203], v[28:31]
	v_mfma_f32_16x16x32_bf16 v[48:51], v[176:179], v[204:207], v[16:19]
	v_mfma_f32_16x16x32_bf16 v[16:19], v[152:155], v[220:223], v[40:43]
	v_mfma_f32_16x16x32_bf16 v[40:43], v[160:163], v[224:227], v[16:19]
	v_mfma_f32_16x16x32_bf16 v[16:19], v[168:171], v[220:223], v[32:35]
	v_mfma_f32_16x16x32_bf16 v[8:11], v[152:155], v[228:231], v[8:11]
	v_mfma_f32_16x16x32_bf16 v[0:3], v[168:171], v[228:231], v[0:3]
	v_mfma_f32_16x16x32_bf16 v[32:35], v[176:179], v[224:227], v[16:19]
	v_mfma_f32_16x16x32_bf16 v[8:11], v[160:163], v[246:249], v[8:11]
	v_mfma_f32_16x16x32_bf16 v[0:3], v[176:179], v[246:249], v[0:3]
	s_setprio 0
	s_barrier
	s_add_i32 s6, s6, 2
	s_add_i32 s4, s4, 0x8000
	s_add_i32 s5, s5, 0x8000
	s_cmp_gt_u32 s6, 29
	s_cbranch_scc0 .LBB0_143
.LBB0_146:
	s_lshl_b32 s18, s15, 8
	s_cmp_lt_i32 s15, 4
	s_cbranch_scc1 .LBB0_155
	s_cmp_eq_u32 s15, 4
	s_cbranch_scc1 .LBB0_156
	s_cmp_gt_u32 s15, 5
	s_mov_b64 s[4:5], -1
	s_cbranch_scc0 .LBB0_153
	s_mov_b64 s[0:1], -1
	s_cmp_gt_u32 s15, 13
	s_mov_b64 s[6:7], -1
	s_cbranch_scc0 .LBB0_151
	s_add_i32 s4, s18, 0xfffff200
	s_lshr_b32 s88, s4, 1
	s_mov_b64 s[6:7], 0

.LBB0_158:
	s_xor_b64 s[48:49], s[0:1], -1
	s_cmpk_gt_i32 s88, 0x3ff
	s_cselect_b64 s[28:29], -1, 0
	s_lshl_b32 s19, s14, 11
	s_add_i32 s4, s88, 0xe00
	s_and_b64 s[0:1], s[0:1], exec
	s_cselect_b32 s0, s4, s18
	v_add_u32_e32 v16, s0, v244
	s_movk_i32 s0, 0x2000
	v_ashrrev_i32_e32 v17, 31, v16
	s_cselect_b32 s34, s0, 0x200
	s_cmp_lt_i32 s15, 5
	v_lshl_add_u64 v[20:21], v[16:17], 2, s[8:9]
	s_cselect_b64 s[0:1], -1, 0
	v_lshl_add_u64 v[28:29], v[20:21], 0, s[34:35]
	s_and_b64 s[4:5], s[12:13], s[0:1]
	s_lshl_b32 s34, s14, 8
	s_add_u32 s0, s71, s19
	s_addc_u32 s1, s72, 0
	s_mov_b64 s[18:19], s[0:1]
	global_load_dwordx4 v[16:19], v[20:21], off offset:16
	global_load_dwordx4 v[24:27], v[20:21], off
	s_nop 0
	global_load_dwordx4 v[20:23], v[28:29], off offset:16
	s_nop 0
	global_load_dwordx4 v[28:31], v[28:29], off
	v_mul_lo_u32 v80, s89, v82
	v_lshl_add_u64 v[152:153], s[18:19], 0, v[186:187]
	s_add_u32 s18, s0, 0x80
	s_addc_u32 s19, s1, 0
	global_load_dwordx2 v[152:153], v[152:153], off
	v_or_b32_e32 v80, v80, v244
	v_lshl_add_u64 v[154:155], s[18:19], 0, v[186:187]
	s_add_u32 s18, s0, 0x100
	s_addc_u32 s19, s1, 0
	global_load_dwordx2 v[204:205], v[154:155], off
	v_lshlrev_b32_e32 v80, 1, v80
	v_lshl_add_u64 v[154:155], s[18:19], 0, v[186:187]
	s_add_u32 s18, s0, 0x180
	s_addc_u32 s19, s1, 0
	global_load_dwordx2 v[202:203], v[154:155], off
	s_and_b64 vcc, exec, s[10:11]
	s_cbranch_vccz .Lab_p1
	s_barrier
.Lab_p1:
	s_waitcnt vmcnt(2)
	v_cvt_f32_u32_e32 v153, v153
	v_lshl_add_u64 v[154:155], s[18:19], 0, v[186:187]
	s_add_u32 s18, s0, 0x400
	s_addc_u32 s19, s1, 0
	global_load_dwordx2 v[200:201], v[154:155], off
	v_cvt_f32_u32_e32 v152, v152
	v_lshl_add_u64 v[154:155], s[18:19], 0, v[186:187]
	s_add_u32 s18, s0, 0x480
	s_addc_u32 s19, s1, 0
	global_load_dwordx2 v[198:199], v[154:155], off
	v_fmac_f32_e32 v152, 0x4f800000, v153
	v_lshl_add_u64 v[154:155], s[18:19], 0, v[186:187]
	s_add_u32 s18, s0, 0x500
	s_addc_u32 s19, s1, 0
	s_add_u32 s0, s0, 0x580
	global_load_dwordx2 v[196:197], v[154:155], off
	s_addc_u32 s1, s1, 0
	v_lshl_add_u64 v[154:155], s[18:19], 0, v[186:187]
	global_load_dwordx2 v[194:195], v[154:155], off
	v_fmamk_f32 v152, v152, 0x30000000, v234
	v_lshl_add_u64 v[154:155], s[0:1], 0, v[186:187]
	global_load_dwordx2 v[192:193], v[154:155], off
	v_rsq_f32_e32 v206, v152
	v_cndmask_b32_e64 v152, 0, 1, s[4:5]
	s_mov_b64 s[0:1], -1
	s_and_b64 s[18:19], s[6:7], s[28:29]
	s_lshl_b32 s90, s14, 14
	s_and_b64 vcc, exec, s[48:49]
	v_cmp_ne_u32_e64 s[42:43], 1, v152
	s_cbranch_vccz .LBB0_182
	s_and_b64 vcc, exec, s[42:43]
	s_cbranch_vccnz .LBB0_163
	v_readlane_b32 s0, v250, 28
	v_readlane_b32 s1, v250, 29
	s_add_u32 s0, s0, s90
	s_addc_u32 s1, s1, 0
	s_mov_b64 s[4:5], s[0:1]
	s_nop 0
	v_lshl_add_u64 v[152:153], s[4:5], 0, v[184:185]
	s_add_u32 s4, s0, 16
	s_addc_u32 s5, s1, 0
	global_load_dwordx4 v[152:155], v[152:153], off
	s_nop 0
	v_lshl_add_u64 v[160:161], s[4:5], 0, v[184:185]
	s_add_u32 s4, s0, 32
	s_addc_u32 s5, s1, 0
	s_add_u32 s0, s0, 48
	global_load_dwordx4 v[160:163], v[160:161], off
	s_addc_u32 s1, s1, 0
	v_lshl_add_u64 v[168:169], s[4:5], 0, v[184:185]
	global_load_dwordx4 v[168:171], v[168:169], off
	s_nop 0
	v_lshl_add_u64 v[176:177], s[0:1], 0, v[184:185]
	global_load_dwordx4 v[176:179], v[176:177], off
	s_and_saveexec_b64 s[0:1], s[36:37]
	s_cbranch_execz .LBB0_162
	s_waitcnt vmcnt(0)
	v_xor_b32_e32 v179, 0x80000000, v179
	v_xor_b32_e32 v178, 0x80000000, v178
	v_xor_b32_e32 v177, 0x80000000, v177
	v_xor_b32_e32 v176, 0x80000000, v176
	v_xor_b32_e32 v171, 0x80000000, v171
	v_xor_b32_e32 v170, 0x80000000, v170
	v_xor_b32_e32 v169, 0x80000000, v169
	v_xor_b32_e32 v168, 0x80000000, v168

.LBB0_599:
	v_readlane_b32 s8, v252, 45
	s_add_u32 s4, s8, s91
	v_readlane_b32 s9, v252, 46
	s_addc_u32 s5, s9, 0
	s_nop 0
	v_lshl_add_u64 v[82:83], s[4:5], 0, v[220:221]
	global_load_dwordx4 v[228:231], v[82:83], off
	s_add_u32 s4, s8, s90
	s_addc_u32 s5, s9, 0
	s_add_u32 s6, s8, s88
	v_lshl_add_u64 v[82:83], s[4:5], 0, v[220:221]
	global_load_dwordx4 v[240:243], v[82:83], off
	s_addc_u32 s7, s9, 0
	s_add_u32 s4, s8, s81
	v_lshl_add_u64 v[82:83], s[6:7], 0, v[220:221]
	global_load_dwordx4 v[204:207], v[82:83], off
	s_addc_u32 s5, s9, 0
	s_add_u32 s6, s8, s80
	v_lshl_add_u64 v[82:83], s[4:5], 0, v[220:221]
	global_load_dwordx4 v[200:203], v[82:83], off
	s_addc_u32 s7, s9, 0
	s_add_u32 s4, s8, s89
	v_lshl_add_u64 v[82:83], s[6:7], 0, v[220:221]
	global_load_dwordx4 v[196:199], v[82:83], off
	s_addc_u32 s5, s9, 0
	s_add_u32 s6, s8, s33
	v_lshl_add_u64 v[82:83], s[4:5], 0, v[220:221]
	global_load_dwordx4 v[192:195], v[82:83], off
	s_addc_u32 s7, s9, 0
	s_add_u32 s4, s8, s3
	v_lshl_add_u64 v[82:83], s[6:7], 0, v[220:221]
	global_load_dwordx4 v[188:191], v[82:83], off
	s_addc_u32 s5, s9, 0
	s_add_u32 s2, s8, s2
	v_lshl_add_u64 v[82:83], s[4:5], 0, v[220:221]
	global_load_dwordx4 v[184:187], v[82:83], off
	s_addc_u32 s3, s9, 0
	s_add_u32 s4, s8, s1
	v_lshl_add_u64 v[82:83], s[2:3], 0, v[220:221]
	global_load_dwordx4 v[180:183], v[82:83], off
	s_addc_u32 s5, s9, 0
	s_add_u32 s0, s8, s0
	v_lshl_add_u64 v[82:83], s[4:5], 0, v[220:221]
	global_load_dwordx4 v[176:179], v[82:83], off
	s_addc_u32 s1, s9, 0
	s_add_u32 s2, s8, s37
	v_lshl_add_u64 v[82:83], s[0:1], 0, v[220:221]
	global_load_dwordx4 v[172:175], v[82:83], off
	s_addc_u32 s3, s9, 0
	v_readlane_b32 s0, v254, 41
	v_lshl_add_u64 v[82:83], s[2:3], 0, v[220:221]
	global_load_dwordx4 v[168:171], v[82:83], off
	s_add_u32 s0, s8, s0
	s_addc_u32 s1, s9, 0
	v_readlane_b32 s2, v254, 39
	v_lshl_add_u64 v[82:83], s[0:1], 0, v[220:221]
	global_load_dwordx4 v[164:167], v[82:83], off
	s_add_u32 s2, s8, s2
	s_addc_u32 s3, s9, 0
	v_readlane_b32 s0, v254, 37
	v_lshl_add_u64 v[82:83], s[2:3], 0, v[220:221]
	global_load_dwordx4 v[160:163], v[82:83], off
	s_add_u32 s0, s8, s0
	s_addc_u32 s1, s9, 0
	v_readlane_b32 s2, v254, 35
	v_lshl_add_u64 v[82:83], s[0:1], 0, v[220:221]
	global_load_dwordx4 v[156:159], v[82:83], off
	s_add_u32 s2, s8, s2
	s_addc_u32 s3, s9, 0
	s_lshl_b32 s0, s92, 16
	v_lshl_add_u64 v[82:83], s[2:3], 0, v[220:221]
	global_load_dwordx4 v[152:155], v[82:83], off
	v_readlane_b32 s1, v254, 33
	s_add_i32 s0, s1, s0
	v_readlane_b32 s8, v254, 10
	v_readlane_b32 s98, v254, 43
	v_readlane_b32 s99, v254, 44
	s_and_b64 vcc, exec, s[98:99]
	s_cbranch_vccz .Lab_p3
	s_barrier
.Lab_p3:
	s_waitcnt vmcnt(15)
	v_lshlrev_b32_e32 v82, 16, v228
	v_and_b32_e32 v83, 0xffff0000, v228
	v_lshlrev_b32_e32 v208, 16, v229
	v_and_b32_e32 v209, 0xffff0000, v229
	s_add_u32 s2, s8, s0
	v_readlane_b32 s6, v252, 49
	v_pk_mul_f32 v[150:151], v[150:151], v[208:209]
	v_pk_mul_f32 v[82:83], v[148:149], v[82:83]
	v_lshlrev_b32_e32 v148, 16, v230
	v_and_b32_e32 v149, 0xffff0000, v230
	v_lshlrev_b32_e32 v208, 16, v231
	v_and_b32_e32 v209, 0xffff0000, v231
	s_addc_u32 s3, s6, 0
	v_pk_mul_f32 v[208:209], v[146:147], v[208:209]
	v_pk_mul_f32 v[146:147], v[144:145], v[148:149]
	s_mov_b64 s[4:5], s[2:3]
	v_cvt_pk_bf16_f32 v144, v82, v83
	v_cvt_pk_bf16_f32 v145, v150, v151
	v_cvt_pk_bf16_f32 v146, v146, v147
	v_cvt_pk_bf16_f32 v147, v208, v209
	s_or_b32 s1, s0, 0x8000
	v_lshl_add_u64 v[82:83], s[4:5], 0, v[222:223]
	global_store_dwordx4 v[82:83], v[144:147], off
	s_waitcnt vmcnt(15)
	v_lshlrev_b32_e32 v82, 16, v240
	v_and_b32_e32 v83, 0xffff0000, v240
	v_lshlrev_b32_e32 v144, 16, v241
	v_and_b32_e32 v145, 0xffff0000, v241
	v_pk_mul_f32 v[142:143], v[142:143], v[144:145]
	v_pk_mul_f32 v[82:83], v[140:141], v[82:83]
	v_lshlrev_b32_e32 v140, 16, v242
	v_and_b32_e32 v141, 0xffff0000, v242
	v_lshlrev_b32_e32 v144, 16, v243
	v_and_b32_e32 v145, 0xffff0000, v243
	s_add_u32 s4, s8, s1
	v_pk_mul_f32 v[144:145], v[138:139], v[144:145]
	v_pk_mul_f32 v[138:139], v[136:137], v[140:141]
	s_addc_u32 s5, s6, 0
	v_cvt_pk_bf16_f32 v136, v82, v83
	v_cvt_pk_bf16_f32 v137, v142, v143
	v_cvt_pk_bf16_f32 v138, v138, v139
	v_cvt_pk_bf16_f32 v139, v144, v145
	s_add_u32 s2, s2, 0x800
	v_lshl_add_u64 v[82:83], s[4:5], 0, v[222:223]
	global_store_dwordx4 v[82:83], v[136:139], off
	s_waitcnt vmcnt(15)
	v_lshlrev_b32_e32 v82, 16, v204
	v_and_b32_e32 v83, 0xffff0000, v204
	v_lshlrev_b32_e32 v136, 16, v205
	v_and_b32_e32 v137, 0xffff0000, v205
	v_pk_mul_f32 v[134:135], v[134:135], v[136:137]
	v_pk_mul_f32 v[82:83], v[132:133], v[82:83]
	v_lshlrev_b32_e32 v132, 16, v206
	v_and_b32_e32 v133, 0xffff0000, v206
	v_lshlrev_b32_e32 v136, 16, v207
	v_and_b32_e32 v137, 0xffff0000, v207
	v_pk_mul_f32 v[136:137], v[130:131], v[136:137]
	v_pk_mul_f32 v[130:131], v[128:129], v[132:133]
	s_addc_u32 s3, s3, 0
	v_cvt_pk_bf16_f32 v128, v82, v83
	v_cvt_pk_bf16_f32 v129, v134, v135
	v_cvt_pk_bf16_f32 v130, v130, v131
	v_cvt_pk_bf16_f32 v131, v136, v137
	s_or_b32 s1, s0, 0x8800
	v_lshl_add_u64 v[82:83], s[2:3], 0, v[222:223]
	global_store_dwordx4 v[82:83], v[128:131], off
	s_waitcnt vmcnt(15)
	v_lshlrev_b32_e32 v82, 16, v200
	v_and_b32_e32 v83, 0xffff0000, v200
	v_lshlrev_b32_e32 v128, 16, v201
	v_and_b32_e32 v129, 0xffff0000, v201
	v_pk_mul_f32 v[126:127], v[126:127], v[128:129]
	v_pk_mul_f32 v[82:83], v[124:125], v[82:83]
	v_lshlrev_b32_e32 v124, 16, v202
	v_and_b32_e32 v125, 0xffff0000, v202
	v_lshlrev_b32_e32 v128, 16, v203
	v_and_b32_e32 v129, 0xffff0000, v203
	s_add_u32 s2, s8, s1
	v_pk_mul_f32 v[128:129], v[122:123], v[128:129]
	v_pk_mul_f32 v[122:123], v[120:121], v[124:125]
	s_addc_u32 s3, s6, 0
	v_cvt_pk_bf16_f32 v120, v82, v83
	v_cvt_pk_bf16_f32 v121, v126, v127
	v_cvt_pk_bf16_f32 v122, v122, v123
	v_cvt_pk_bf16_f32 v123, v128, v129
	s_or_b32 s1, s0, 0x1000
	v_lshl_add_u64 v[82:83], s[2:3], 0, v[222:223]
	global_store_dwordx4 v[82:83], v[120:123], off
	s_waitcnt vmcnt(15)
	v_lshlrev_b32_e32 v82, 16, v196
	v_and_b32_e32 v83, 0xffff0000, v196
	v_lshlrev_b32_e32 v120, 16, v197
	v_and_b32_e32 v121, 0xffff0000, v197
	v_pk_mul_f32 v[118:119], v[118:119], v[120:121]
	v_pk_mul_f32 v[82:83], v[116:117], v[82:83]
	v_lshlrev_b32_e32 v116, 16, v198
	v_and_b32_e32 v117, 0xffff0000, v198
	v_lshlrev_b32_e32 v120, 16, v199
	v_and_b32_e32 v121, 0xffff0000, v199
	s_add_u32 s2, s8, s1
	v_pk_mul_f32 v[120:121], v[114:115], v[120:121]
	v_pk_mul_f32 v[114:115], v[112:113], v[116:117]
	s_addc_u32 s3, s6, 0
	v_cvt_pk_bf16_f32 v112, v82, v83
	v_cvt_pk_bf16_f32 v113, v118, v119
	v_cvt_pk_bf16_f32 v114, v114, v115
	v_cvt_pk_bf16_f32 v115, v120, v121
	s_or_b32 s1, s0, 0x9000
	v_lshl_add_u64 v[82:83], s[2:3], 0, v[222:223]
	global_store_dwordx4 v[82:83], v[112:115], off
	s_waitcnt vmcnt(15)
	v_lshlrev_b32_e32 v82, 16, v192
	v_and_b32_e32 v83, 0xffff0000, v192
	v_lshlrev_b32_e32 v112, 16, v193
	v_and_b32_e32 v113, 0xffff0000, v193
	v_pk_mul_f32 v[110:111], v[110:111], v[112:113]
	v_pk_mul_f32 v[82:83], v[108:109], v[82:83]
	v_lshlrev_b32_e32 v108, 16, v194
	v_and_b32_e32 v109, 0xffff0000, v194
	v_lshlrev_b32_e32 v112, 16, v195
	v_and_b32_e32 v113, 0xffff0000, v195
	s_add_u32 s2, s8, s1
	v_pk_mul_f32 v[112:113], v[106:107], v[112:113]
	v_pk_mul_f32 v[106:107], v[104:105], v[108:109]
	s_addc_u32 s3, s6, 0
	v_cvt_pk_bf16_f32 v104, v82, v83
	v_cvt_pk_bf16_f32 v105, v110, v111
	v_cvt_pk_bf16_f32 v106, v106, v107
	v_cvt_pk_bf16_f32 v107, v112, v113
	s_or_b32 s1, s0, 0x1800
	v_lshl_add_u64 v[82:83], s[2:3], 0, v[222:223]
	global_store_dwordx4 v[82:83], v[104:107], off
	s_waitcnt vmcnt(15)
	v_lshlrev_b32_e32 v82, 16, v188
	v_and_b32_e32 v83, 0xffff0000, v188
	v_lshlrev_b32_e32 v104, 16, v189
	v_and_b32_e32 v105, 0xffff0000, v189
	v_pk_mul_f32 v[78:79], v[78:79], v[104:105]
	v_pk_mul_f32 v[76:77], v[76:77], v[82:83]
	v_lshlrev_b32_e32 v82, 16, v190
	v_and_b32_e32 v83, 0xffff0000, v190
	v_lshlrev_b32_e32 v104, 16, v191
	v_and_b32_e32 v105, 0xffff0000, v191
	s_add_u32 s2, s8, s1
	v_pk_mul_f32 v[104:105], v[74:75], v[104:105]
	v_pk_mul_f32 v[74:75], v[72:73], v[82:83]
	s_addc_u32 s3, s6, 0
	v_cvt_pk_bf16_f32 v72, v76, v77
	v_cvt_pk_bf16_f32 v73, v78, v79
	v_cvt_pk_bf16_f32 v74, v74, v75
	v_cvt_pk_bf16_f32 v75, v104, v105
	s_or_b32 s1, s0, 0x9800
	v_lshl_add_u64 v[76:77], s[2:3], 0, v[222:223]
	global_store_dwordx4 v[76:77], v[72:75], off
	s_add_u32 s2, s8, s1
	s_addc_u32 s3, s6, 0
	s_waitcnt vmcnt(15)
	v_lshlrev_b32_e32 v72, 16, v184
	v_and_b32_e32 v73, 0xffff0000, v184
	v_lshlrev_b32_e32 v74, 16, v185
	v_and_b32_e32 v75, 0xffff0000, v185
	v_pk_mul_f32 v[70:71], v[70:71], v[74:75]
	v_pk_mul_f32 v[68:69], v[68:69], v[72:73]
	v_lshlrev_b32_e32 v72, 16, v186
	v_and_b32_e32 v73, 0xffff0000, v186
	v_lshlrev_b32_e32 v74, 16, v187
	v_and_b32_e32 v75, 0xffff0000, v187
	v_pk_mul_f32 v[74:75], v[66:67], v[74:75]
	v_pk_mul_f32 v[66:67], v[64:65], v[72:73]
	v_cvt_pk_bf16_f32 v64, v68, v69
	v_cvt_pk_bf16_f32 v65, v70, v71
	v_cvt_pk_bf16_f32 v66, v66, v67
	v_cvt_pk_bf16_f32 v67, v74, v75
	s_add_i32 s1, s0, 0x80000
	v_lshl_add_u64 v[68:69], s[2:3], 0, v[222:223]
	global_store_dwordx4 v[68:69], v[64:67], off
	s_add_u32 s2, s8, s1
	s_addc_u32 s3, s6, 0
	s_waitcnt vmcnt(15)
	v_lshlrev_b32_e32 v64, 16, v180
	v_and_b32_e32 v65, 0xffff0000, v180
	v_lshlrev_b32_e32 v66, 16, v181
	v_and_b32_e32 v67, 0xffff0000, v181
	v_pk_mul_f32 v[62:63], v[62:63], v[66:67]
	v_pk_mul_f32 v[60:61], v[60:61], v[64:65]
	v_lshlrev_b32_e32 v64, 16, v182
	v_and_b32_e32 v65, 0xffff0000, v182
	v_lshlrev_b32_e32 v66, 16, v183
	v_and_b32_e32 v67, 0xffff0000, v183
	v_pk_mul_f32 v[66:67], v[58:59], v[66:67]
	v_pk_mul_f32 v[58:59], v[56:57], v[64:65]
	v_cvt_pk_bf16_f32 v56, v60, v61
	v_cvt_pk_bf16_f32 v57, v62, v63
	v_cvt_pk_bf16_f32 v58, v58, v59
	v_cvt_pk_bf16_f32 v59, v66, v67
	s_add_i32 s1, s0, 0x88000
	v_lshl_add_u64 v[60:61], s[2:3], 0, v[222:223]
	global_store_dwordx4 v[60:61], v[56:59], off
	s_add_u32 s2, s8, s1
	s_addc_u32 s3, s6, 0
	s_waitcnt vmcnt(15)
	v_lshlrev_b32_e32 v56, 16, v176
	v_and_b32_e32 v57, 0xffff0000, v176
	v_lshlrev_b32_e32 v58, 16, v177
	v_and_b32_e32 v59, 0xffff0000, v177
	v_pk_mul_f32 v[54:55], v[54:55], v[58:59]
	v_pk_mul_f32 v[52:53], v[52:53], v[56:57]
	v_lshlrev_b32_e32 v56, 16, v178
	v_and_b32_e32 v57, 0xffff0000, v178
	v_lshlrev_b32_e32 v58, 16, v179
	v_and_b32_e32 v59, 0xffff0000, v179
	v_pk_mul_f32 v[58:59], v[50:51], v[58:59]
	v_pk_mul_f32 v[50:51], v[48:49], v[56:57]
	v_cvt_pk_bf16_f32 v48, v52, v53
	v_cvt_pk_bf16_f32 v49, v54, v55
	v_cvt_pk_bf16_f32 v50, v50, v51
	v_cvt_pk_bf16_f32 v51, v58, v59
	s_add_i32 s1, s0, 0x80800
	v_lshl_add_u64 v[52:53], s[2:3], 0, v[222:223]
	global_store_dwordx4 v[52:53], v[48:51], off
	s_add_u32 s2, s8, s1
	s_addc_u32 s3, s6, 0
	s_waitcnt vmcnt(15)
	v_lshlrev_b32_e32 v48, 16, v172
	v_and_b32_e32 v49, 0xffff0000, v172
	v_lshlrev_b32_e32 v50, 16, v173
	v_and_b32_e32 v51, 0xffff0000, v173
	v_pk_mul_f32 v[46:47], v[46:47], v[50:51]
	v_pk_mul_f32 v[44:45], v[44:45], v[48:49]
	v_lshlrev_b32_e32 v48, 16, v174
	v_and_b32_e32 v49, 0xffff0000, v174
	v_lshlrev_b32_e32 v50, 16, v175
	v_and_b32_e32 v51, 0xffff0000, v175
	v_pk_mul_f32 v[50:51], v[42:43], v[50:51]
	v_pk_mul_f32 v[42:43], v[40:41], v[48:49]
	v_cvt_pk_bf16_f32 v40, v44, v45
	v_cvt_pk_bf16_f32 v41, v46, v47
	v_cvt_pk_bf16_f32 v42, v42, v43
	v_cvt_pk_bf16_f32 v43, v50, v51
	s_add_i32 s1, s0, 0x88800
	v_lshl_add_u64 v[44:45], s[2:3], 0, v[222:223]
	global_store_dwordx4 v[44:45], v[40:43], off
	s_add_u32 s2, s8, s1
	s_addc_u32 s3, s6, 0
	s_waitcnt vmcnt(15)
	v_lshlrev_b32_e32 v40, 16, v168
	v_and_b32_e32 v41, 0xffff0000, v168
	v_lshlrev_b32_e32 v42, 16, v169
	v_and_b32_e32 v43, 0xffff0000, v169
	v_pk_mul_f32 v[38:39], v[38:39], v[42:43]
	v_pk_mul_f32 v[36:37], v[36:37], v[40:41]
	v_lshlrev_b32_e32 v40, 16, v170
	v_and_b32_e32 v41, 0xffff0000, v170
	v_lshlrev_b32_e32 v42, 16, v171
	v_and_b32_e32 v43, 0xffff0000, v171
	v_pk_mul_f32 v[42:43], v[34:35], v[42:43]
	v_pk_mul_f32 v[34:35], v[32:33], v[40:41]
	v_cvt_pk_bf16_f32 v32, v36, v37
	v_cvt_pk_bf16_f32 v33, v38, v39
	v_cvt_pk_bf16_f32 v34, v34, v35
	v_cvt_pk_bf16_f32 v35, v42, v43
	s_add_i32 s1, s0, 0x81000
	v_lshl_add_u64 v[36:37], s[2:3], 0, v[222:223]
	global_store_dwordx4 v[36:37], v[32:35], off
	s_add_u32 s2, s8, s1
	s_addc_u32 s3, s6, 0
	s_waitcnt vmcnt(15)
	v_lshlrev_b32_e32 v32, 16, v164
	v_and_b32_e32 v33, 0xffff0000, v164
	v_lshlrev_b32_e32 v34, 16, v165
	v_and_b32_e32 v35, 0xffff0000, v165
	v_pk_mul_f32 v[30:31], v[30:31], v[34:35]
	v_pk_mul_f32 v[28:29], v[28:29], v[32:33]
	v_lshlrev_b32_e32 v32, 16, v166
	v_and_b32_e32 v33, 0xffff0000, v166
	v_lshlrev_b32_e32 v34, 16, v167
	v_and_b32_e32 v35, 0xffff0000, v167
	v_pk_mul_f32 v[34:35], v[26:27], v[34:35]
	v_pk_mul_f32 v[26:27], v[24:25], v[32:33]
	v_cvt_pk_bf16_f32 v24, v28, v29
	v_cvt_pk_bf16_f32 v25, v30, v31
	v_cvt_pk_bf16_f32 v26, v26, v27
	v_cvt_pk_bf16_f32 v27, v34, v35
	s_add_i32 s1, s0, 0x89000
	v_lshl_add_u64 v[28:29], s[2:3], 0, v[222:223]
	global_store_dwordx4 v[28:29], v[24:27], off
	s_add_u32 s2, s8, s1
	s_addc_u32 s3, s6, 0
	s_waitcnt vmcnt(15)
	v_lshlrev_b32_e32 v24, 16, v160
	v_and_b32_e32 v25, 0xffff0000, v160
	v_lshlrev_b32_e32 v26, 16, v161
	v_and_b32_e32 v27, 0xffff0000, v161
	v_pk_mul_f32 v[22:23], v[22:23], v[26:27]
	v_pk_mul_f32 v[20:21], v[20:21], v[24:25]
	v_lshlrev_b32_e32 v24, 16, v162
	v_and_b32_e32 v25, 0xffff0000, v162
	v_lshlrev_b32_e32 v26, 16, v163
	v_and_b32_e32 v27, 0xffff0000, v163
	v_pk_mul_f32 v[26:27], v[18:19], v[26:27]
	v_pk_mul_f32 v[18:19], v[16:17], v[24:25]
	v_cvt_pk_bf16_f32 v16, v20, v21
	v_cvt_pk_bf16_f32 v17, v22, v23
	v_cvt_pk_bf16_f32 v18, v18, v19
	v_cvt_pk_bf16_f32 v19, v26, v27
	s_add_i32 s1, s0, 0x81800
	v_lshl_add_u64 v[20:21], s[2:3], 0, v[222:223]
	global_store_dwordx4 v[20:21], v[16:19], off
	s_add_u32 s2, s8, s1
	s_addc_u32 s3, s6, 0
	s_waitcnt vmcnt(15)
	v_lshlrev_b32_e32 v16, 16, v156
	v_and_b32_e32 v17, 0xffff0000, v156
	v_lshlrev_b32_e32 v18, 16, v157
	v_and_b32_e32 v19, 0xffff0000, v157
	v_pk_mul_f32 v[14:15], v[14:15], v[18:19]
	v_pk_mul_f32 v[12:13], v[12:13], v[16:17]
	v_lshlrev_b32_e32 v16, 16, v158
	v_and_b32_e32 v17, 0xffff0000, v158
	v_lshlrev_b32_e32 v18, 16, v159
	v_and_b32_e32 v19, 0xffff0000, v159
	v_pk_mul_f32 v[18:19], v[10:11], v[18:19]
	v_pk_mul_f32 v[10:11], v[8:9], v[16:17]
	s_add_i32 s0, s0, 0x89800
	v_cvt_pk_bf16_f32 v8, v12, v13
	v_cvt_pk_bf16_f32 v9, v14, v15
	v_cvt_pk_bf16_f32 v10, v10, v11
	v_cvt_pk_bf16_f32 v11, v18, v19
	s_add_u32 s0, s8, s0
	v_lshl_add_u64 v[12:13], s[2:3], 0, v[222:223]
	global_store_dwordx4 v[12:13], v[8:11], off
	s_addc_u32 s1, s6, 0
	s_mov_b64 s[4:5], -1
	s_waitcnt vmcnt(15)
	v_lshlrev_b32_e32 v8, 16, v152
	v_and_b32_e32 v9, 0xffff0000, v152
	v_lshlrev_b32_e32 v10, 16, v153
	v_and_b32_e32 v11, 0xffff0000, v153
	v_pk_mul_f32 v[6:7], v[6:7], v[10:11]
	v_pk_mul_f32 v[4:5], v[4:5], v[8:9]
	v_lshlrev_b32_e32 v8, 16, v154
	v_and_b32_e32 v9, 0xffff0000, v154
	v_lshlrev_b32_e32 v10, 16, v155
	v_and_b32_e32 v11, 0xffff0000, v155
	v_pk_mul_f32 v[10:11], v[2:3], v[10:11]
	v_pk_mul_f32 v[2:3], v[0:1], v[8:9]
	v_cvt_pk_bf16_f32 v0, v4, v5
	v_lshl_add_u64 v[4:5], s[0:1], 0, v[222:223]
	v_readlane_b32 s0, v254, 23
	v_readlane_b32 s1, v254, 24
	v_cvt_pk_bf16_f32 v1, v6, v7
	v_cvt_pk_bf16_f32 v2, v2, v3
	v_cvt_pk_bf16_f32 v3, v10, v11
	s_andn2_b64 vcc, exec, s[0:1]
	v_readlane_b32 s6, v254, 25
	v_readlane_b32 s3, v254, 27
	v_readlane_b32 s9, v254, 11
	v_readlane_b32 s10, v254, 12
	v_readlane_b32 s11, v254, 13
	global_store_dwordx4 v[4:5], v[0:3], off
	s_cbranch_vccnz .LBB0_586
	v_readlane_b32 s0, v254, 45
	v_readlane_b32 s1, v254, 46
	s_andn2_b64 vcc, exec, s[0:1]
	s_cbranch_vccnz .LBB0_585
	s_barrier
	s_branch .LBB0_585

.LBB0_694:
	s_lshl_b32 s5, s5, 16
	s_lshl_b32 s6, s4, 20
	s_add_i32 s5, s6, s5
	s_add_u32 s74, s46, s5
	s_addc_u32 s75, s47, 0
	s_mov_b64 s[6:7], s[74:75]
	s_nop 0
	v_lshl_add_u64 v[128:129], s[6:7], 0, v[80:81]
	s_or_b32 s6, s5, 0x8000
	s_add_u32 s72, s46, s6
	s_addc_u32 s73, s47, 0
	s_mov_b64 s[6:7], s[72:73]
	s_add_u32 s70, s74, 0x800
	global_load_dwordx4 v[224:227], v[128:129], off
	s_addc_u32 s71, s75, 0
	v_lshl_add_u64 v[128:129], s[6:7], 0, v[80:81]
	s_mov_b64 s[6:7], s[70:71]
	global_load_dwordx4 v[228:231], v[128:129], off
	s_and_b64 vcc, exec, s[2:3]
	s_cbranch_vccz .Lab_p4
	s_barrier
.Lab_p4:
	s_waitcnt vmcnt(1)
	v_lshlrev_b32_e32 v208, 16, v224
	v_lshl_add_u64 v[128:129], s[6:7], 0, v[80:81]
	s_or_b32 s6, s5, 0x8800
	s_add_u32 s68, s46, s6
	s_addc_u32 s69, s47, 0
	s_mov_b64 s[6:7], s[68:69]
	global_load_dwordx4 v[204:207], v[128:129], off
	v_and_b32_e32 v209, 0xffff0000, v224
	v_lshl_add_u64 v[128:129], s[6:7], 0, v[80:81]
	s_or_b32 s6, s5, 0x1000
	s_add_u32 s56, s46, s6
	s_addc_u32 s57, s47, 0
	s_mov_b64 s[6:7], s[56:57]
	global_load_dwordx4 v[200:203], v[128:129], off
	v_lshlrev_b32_e32 v210, 16, v225
	v_lshl_add_u64 v[128:129], s[6:7], 0, v[80:81]
	s_or_b32 s6, s5, 0x9000
	s_add_u32 s52, s46, s6
	s_addc_u32 s53, s47, 0
	s_mov_b64 s[6:7], s[52:53]
	global_load_dwordx4 v[196:199], v[128:129], off
	v_and_b32_e32 v211, 0xffff0000, v225
	v_lshl_add_u64 v[128:129], s[6:7], 0, v[80:81]
	s_or_b32 s6, s5, 0x1800
	s_add_u32 s44, s46, s6
	s_addc_u32 s45, s47, 0
	s_mov_b64 s[6:7], s[44:45]
	global_load_dwordx4 v[192:195], v[128:129], off
	v_pk_add_f32 v[166:167], v[166:167], v[210:211]
	v_lshl_add_u64 v[128:129], s[6:7], 0, v[80:81]
	s_or_b32 s6, s5, 0x9800
	s_add_u32 s42, s46, s6
	s_addc_u32 s43, s47, 0
	s_mov_b64 s[6:7], s[42:43]
	global_load_dwordx4 v[188:191], v[128:129], off
	v_pk_add_f32 v[164:165], v[164:165], v[208:209]
	v_lshl_add_u64 v[128:129], s[6:7], 0, v[80:81]
	s_add_i32 s6, s5, 0x80000
	s_add_u32 s28, s46, s6
	s_addc_u32 s29, s47, 0
	s_mov_b64 s[6:7], s[28:29]
	global_load_dwordx4 v[184:187], v[128:129], off
	v_lshlrev_b32_e32 v208, 16, v226
	v_lshl_add_u64 v[128:129], s[6:7], 0, v[80:81]
	s_add_i32 s6, s5, 0x88000
	s_add_u32 s18, s46, s6
	s_addc_u32 s19, s47, 0
	s_mov_b64 s[6:7], s[18:19]
	global_load_dwordx4 v[180:183], v[128:129], off
	v_and_b32_e32 v209, 0xffff0000, v226
	v_lshl_add_u64 v[128:129], s[6:7], 0, v[80:81]
	s_add_i32 s6, s5, 0x80800
	s_add_u32 s16, s46, s6
	s_addc_u32 s17, s47, 0
	s_mov_b64 s[6:7], s[16:17]
	global_load_dwordx4 v[176:179], v[128:129], off
	v_lshlrev_b32_e32 v210, 16, v227
	v_lshl_add_u64 v[128:129], s[6:7], 0, v[80:81]
	s_add_i32 s6, s5, 0x88800
	s_add_u32 s14, s46, s6
	s_addc_u32 s15, s47, 0
	s_mov_b64 s[6:7], s[14:15]
	global_load_dwordx4 v[172:175], v[128:129], off
	v_and_b32_e32 v211, 0xffff0000, v227
	v_lshl_add_u64 v[128:129], s[6:7], 0, v[80:81]
	s_add_i32 s6, s5, 0x81000
	s_add_u32 s12, s46, s6
	s_addc_u32 s13, s47, 0
	s_mov_b64 s[6:7], s[12:13]
	global_load_dwordx4 v[168:171], v[128:129], off
	v_pk_add_f32 v[210:211], v[162:163], v[210:211]
	v_lshl_add_u64 v[128:129], s[6:7], 0, v[80:81]
	s_add_i32 s6, s5, 0x89000
	s_add_u32 s10, s46, s6
	s_addc_u32 s11, s47, 0
	s_mov_b64 s[6:7], s[10:11]
	global_load_dwordx4 v[156:159], v[128:129], off
	v_pk_add_f32 v[162:163], v[160:161], v[208:209]
	v_lshl_add_u64 v[128:129], s[6:7], 0, v[80:81]
	s_add_i32 s6, s5, 0x81800
	s_add_u32 s8, s46, s6
	s_addc_u32 s9, s47, 0
	s_mov_b64 s[6:7], s[8:9]
	global_load_dwordx4 v[152:155], v[128:129], off
	s_add_i32 s5, s5, 0x89800
	v_lshl_add_u64 v[128:129], s[6:7], 0, v[80:81]
	s_add_u32 s6, s46, s5
	s_addc_u32 s7, s47, 0
	s_mov_b64 s[36:37], s[6:7]
	global_load_dwordx4 v[140:143], v[128:129], off
	v_mul_f32_e32 v160, v165, v165
	v_lshl_add_u64 v[128:129], s[36:37], 0, v[80:81]
	global_load_dwordx4 v[128:131], v[128:129], off
	v_mul_f32_e32 v161, v167, v167
	v_fmac_f32_e32 v160, v164, v164
	v_fmac_f32_e32 v161, v166, v166
	v_add_f32_e32 v160, v160, v161
	v_mul_f32_e32 v161, v163, v163
	v_fmac_f32_e32 v161, v162, v162
	v_add_f32_e32 v160, v161, v160
	v_mul_f32_e32 v161, v211, v211
	v_fmac_f32_e32 v161, v210, v210
	v_add_f32_e32 v208, v161, v160
	v_cvt_pk_bf16_f32 v160, v164, v165
	v_cvt_pk_bf16_f32 v161, v166, v167
	v_cvt_pk_bf16_f32 v162, v162, v163
	v_cvt_pk_bf16_f32 v163, v210, v211
	s_ashr_i32 s5, s4, 31
	v_lshl_add_u64 v[164:165], s[74:75], 0, v[80:81]
	global_store_dwordx4 v[164:165], v[160:163], off
	s_lshl_b64 s[4:5], s[4:5], 11
	s_waitcnt vmcnt(15)
	v_lshlrev_b32_e32 v160, 16, v228
	v_and_b32_e32 v161, 0xffff0000, v228
	v_lshlrev_b32_e32 v162, 16, v229
	v_and_b32_e32 v163, 0xffff0000, v229
	v_pk_add_f32 v[150:151], v[150:151], v[162:163]
	v_pk_add_f32 v[148:149], v[148:149], v[160:161]
	v_lshlrev_b32_e32 v162, 16, v231
	v_and_b32_e32 v163, 0xffff0000, v231
	v_lshlrev_b32_e32 v160, 16, v230
	v_and_b32_e32 v161, 0xffff0000, v230
	v_pk_add_f32 v[164:165], v[146:147], v[162:163]
	v_mul_f32_e32 v146, v149, v149
	v_mul_f32_e32 v147, v151, v151
	v_pk_add_f32 v[144:145], v[144:145], v[160:161]
	v_fmac_f32_e32 v146, v148, v148
	v_fmac_f32_e32 v147, v150, v150
	v_add_f32_e32 v146, v146, v147
	v_mul_f32_e32 v147, v145, v145
	v_fmac_f32_e32 v147, v144, v144
	v_add_f32_e32 v146, v147, v146
	v_mul_f32_e32 v147, v165, v165
	v_fmac_f32_e32 v147, v164, v164
	v_add_f32_e32 v146, v147, v146
	v_and_b32_e32 v160, 64, v237
	v_add_f32_e32 v147, v208, v146
	v_xor_b32_e32 v146, 16, v237
	v_add_u32_e32 v166, 64, v160
	v_cmp_lt_i32_e32 vcc, v146, v166
	v_cvt_pk_bf16_f32 v162, v144, v145
	v_xor_b32_e32 v144, 32, v237
	v_cndmask_b32_e32 v146, v237, v146, vcc
	v_lshlrev_b32_e32 v146, 2, v146
	ds_bpermute_b32 v167, v146, v147
	v_cmp_lt_i32_e32 vcc, v144, v166
	v_cvt_pk_bf16_f32 v160, v148, v149
	v_cvt_pk_bf16_f32 v161, v150, v151
	v_cndmask_b32_e32 v144, v237, v144, vcc
	s_waitcnt lgkmcnt(0)
	v_add_f32_e32 v148, v147, v167
	v_lshlrev_b32_e32 v147, 2, v144
	ds_bpermute_b32 v149, v147, v148
	v_cvt_pk_bf16_f32 v163, v164, v165
	v_lshl_add_u64 v[144:145], s[72:73], 0, v[80:81]
	global_store_dwordx4 v[144:145], v[160:163], off
	v_lshl_add_u64 v[144:145], v[82:83], 0, s[4:5]
	s_and_saveexec_b64 s[4:5], s[38:39]
	s_movk_i32 s72, 0xffe0
	s_cbranch_execz .LBB0_696
	s_waitcnt lgkmcnt(0)
	v_add_f32_e32 v148, v148, v149
	v_cvt_f64_f32_e32 v[148:149], v148
	v_ldexp_f64 v[148:149], v[148:149], 20
	v_trunc_f64_e32 v[148:149], v[148:149]
	v_ldexp_f64 v[150:151], v[148:149], s72
	v_floor_f64_e32 v[150:151], v[150:151]
	v_fmac_f64_e32 v[148:149], 0xc1f00000, v[150:151]
	v_cvt_u32_f64_e32 v148, v[148:149]
	v_cvt_i32_f64_e32 v149, v[150:151]
	global_atomic_add_x2 v[144:145], v[148:149], off

.LBB0_798:
	s_lshl_b32 s51, s36, 15
	s_lshl_b32 s4, s33, 11
	s_add_u32 s4, s14, s4
	s_addc_u32 s5, s15, 0
	s_mov_b64 s[36:37], s[4:5]
	v_pk_mul_f32 v[146:147], v[150:151], v[146:147]
	v_lshl_add_u64 v[152:153], s[36:37], 0, v[80:81]
	global_load_dwordx2 v[170:171], v[152:153], off
	s_add_u32 s36, s4, 0x80
	s_addc_u32 s37, s5, 0
	v_pk_mul_f32 v[144:145], v[148:149], v[144:145]
	v_lshl_add_u64 v[152:153], s[36:37], 0, v[80:81]
	global_load_dwordx2 v[164:165], v[152:153], off
	s_add_u32 s36, s4, 0x100
	s_addc_u32 s37, s5, 0
	s_mul_i32 s33, s33, 0x2c0000
	v_lshl_add_u64 v[152:153], s[36:37], 0, v[80:81]
	global_load_dwordx2 v[162:163], v[152:153], off
	s_add_u32 s36, s4, 0x180
	s_addc_u32 s37, s5, 0
	v_pk_mul_f32 v[138:139], v[142:143], v[138:139]
	v_lshl_add_u64 v[152:153], s[36:37], 0, v[80:81]
	global_load_dwordx2 v[160:161], v[152:153], off
	s_add_u32 s36, s4, 0x400
	s_addc_u32 s37, s5, 0
	v_pk_mul_f32 v[136:137], v[140:141], v[136:137]
	v_lshl_add_u64 v[152:153], s[36:37], 0, v[80:81]
	s_add_u32 s36, s4, 0x480
	s_addc_u32 s37, s5, 0
	global_load_dwordx2 v[158:159], v[152:153], off
	v_pk_mul_f32 v[130:131], v[134:135], v[130:131]
	v_lshl_add_u64 v[152:153], s[36:37], 0, v[80:81]
	s_add_u32 s36, s4, 0x500
	s_addc_u32 s37, s5, 0
	s_add_u32 s4, s4, 0x580
	global_load_dwordx2 v[156:157], v[152:153], off
	s_addc_u32 s5, s5, 0
	v_lshl_add_u64 v[152:153], s[36:37], 0, v[80:81]
	global_load_dwordx2 v[154:155], v[152:153], off
	s_add_i32 s33, s33, s51
	v_lshl_add_u64 v[152:153], s[4:5], 0, v[80:81]
	global_load_dwordx2 v[152:153], v[152:153], off
	s_add_u32 s4, s20, s33
	s_addc_u32 s5, s68, 0
	s_mov_b64 s[36:37], s[4:5]
	v_pk_mul_f32 v[128:129], v[132:133], v[128:129]
	v_pk_mul_f32 v[122:123], v[126:127], v[122:123]
	v_pk_mul_f32 v[120:121], v[124:125], v[120:121]
	s_add_u32 s4, s4, 0x800
	s_addc_u32 s5, s5, 0
	v_pk_mul_f32 v[114:115], v[118:119], v[114:115]
	v_pk_mul_f32 v[112:113], v[116:117], v[112:113]
	v_pk_mul_f32 v[106:107], v[110:111], v[106:107]
	v_pk_mul_f32 v[104:105], v[108:109], v[104:105]
	v_pk_mul_f32 v[74:75], v[78:79], v[74:75]
	v_pk_mul_f32 v[72:73], v[76:77], v[72:73]
	v_pk_mul_f32 v[66:67], v[70:71], v[66:67]
	v_pk_mul_f32 v[64:65], v[68:69], v[64:65]
	v_pk_mul_f32 v[58:59], v[62:63], v[58:59]
	v_pk_mul_f32 v[56:57], v[60:61], v[56:57]
	v_pk_mul_f32 v[50:51], v[54:55], v[50:51]
	v_pk_mul_f32 v[48:49], v[52:53], v[48:49]
	v_pk_mul_f32 v[42:43], v[46:47], v[42:43]
	v_pk_mul_f32 v[40:41], v[44:45], v[40:41]
	v_pk_mul_f32 v[34:35], v[38:39], v[34:35]
	v_pk_mul_f32 v[32:33], v[36:37], v[32:33]
	v_pk_mul_f32 v[26:27], v[30:31], v[26:27]
	v_pk_mul_f32 v[24:25], v[28:29], v[24:25]
	v_pk_mul_f32 v[18:19], v[22:23], v[18:19]
	v_pk_mul_f32 v[16:17], v[20:21], v[16:17]
	v_pk_mul_f32 v[10:11], v[14:15], v[10:11]
	v_pk_mul_f32 v[8:9], v[12:13], v[8:9]
	v_pk_mul_f32 v[2:3], v[6:7], v[2:3]
	v_pk_mul_f32 v[0:1], v[4:5], v[0:1]
	s_and_b64 vcc, exec, s[2:3]
	s_cbranch_vccz .Lab_p5
	s_barrier
.Lab_p5:
	s_waitcnt vmcnt(7)
	v_cvt_f32_u32_e32 v171, v171
	v_cvt_f32_u32_e32 v170, v170
	v_fmac_f32_e32 v170, 0x4f800000, v171
	v_fmamk_f32 v170, v170, 0x30000000, v234
	v_rsq_f32_e32 v178, v170
	s_nop 0
	v_mul_f32_e32 v174, 0xbfb8aa3b, v178
	v_pk_mul_f32 v[172:173], v[150:151], v[174:175] op_sel_hi:[1,0]
	v_pk_mul_f32 v[170:171], v[148:149], v[174:175] op_sel_hi:[1,0]
	v_pk_mul_f32 v[176:177], v[142:143], v[174:175] op_sel_hi:[1,0]
	v_pk_mul_f32 v[174:175], v[140:141], v[174:175] op_sel_hi:[1,0]
	v_mul_f32_e32 v178, v178, v178
	v_pk_mul_f32 v[180:181], v[146:147], v[178:179] op_sel_hi:[1,0]
	v_exp_f32_e32 v170, v170
	v_exp_f32_e32 v174, v174
	v_exp_f32_e32 v171, v171
	v_exp_f32_e32 v175, v175
	v_exp_f32_e32 v172, v172
	v_exp_f32_e32 v176, v176
	v_exp_f32_e32 v173, v173
	v_exp_f32_e32 v177, v177
	v_pk_mul_f32 v[182:183], v[144:145], v[178:179] op_sel_hi:[1,0]
	v_pk_add_f32 v[144:145], v[170:171], 1.0 op_sel_hi:[1,0]
	v_pk_add_f32 v[146:147], v[172:173], 1.0 op_sel_hi:[1,0]
	v_pk_add_f32 v[150:151], v[176:177], 1.0 op_sel_hi:[1,0]
	v_pk_add_f32 v[148:149], v[174:175], 1.0 op_sel_hi:[1,0]
	v_pk_mul_f32 v[138:139], v[138:139], v[178:179] op_sel_hi:[1,0]
	v_pk_mul_f32 v[136:137], v[136:137], v[178:179] op_sel_hi:[1,0]
	v_rcp_f32_e32 v144, v144
	v_rcp_f32_e32 v148, v148
	v_rcp_f32_e32 v145, v145
	v_rcp_f32_e32 v149, v149
	v_rcp_f32_e32 v146, v146
	v_rcp_f32_e32 v150, v150
	v_rcp_f32_e32 v147, v147
	v_rcp_f32_e32 v151, v151
	s_nop 0
	v_pk_mul_f32 v[140:141], v[180:181], v[146:147]
	v_pk_mul_f32 v[142:143], v[182:183], v[144:145]
	v_pk_mul_f32 v[144:145], v[138:139], v[150:151]
	v_pk_mul_f32 v[138:139], v[136:137], v[148:149]
	v_cvt_pk_bf16_f32 v136, v142, v143
	v_cvt_pk_bf16_f32 v137, v140, v141
	v_cvt_pk_bf16_f32 v138, v138, v139
	v_cvt_pk_bf16_f32 v139, v144, v145
	v_lshl_add_u64 v[140:141], s[36:37], 0, v[82:83]
	global_store_dwordx4 v[140:141], v[136:139], off nt
	s_waitcnt vmcnt(7)
	s_nop 0
	v_cvt_f32_u32_e32 v136, v165
	v_cvt_f32_u32_e32 v137, v164
	v_fmac_f32_e32 v137, 0x4f800000, v136
	v_fmamk_f32 v136, v137, 0x30000000, v234
	v_rsq_f32_e32 v144, v136
	s_nop 0
	v_mul_f32_e32 v140, 0xbfb8aa3b, v144
	v_pk_mul_f32 v[138:139], v[134:135], v[140:141] op_sel_hi:[1,0]
	v_pk_mul_f32 v[136:137], v[132:133], v[140:141] op_sel_hi:[1,0]
	v_pk_mul_f32 v[142:143], v[126:127], v[140:141] op_sel_hi:[1,0]
	v_pk_mul_f32 v[140:141], v[124:125], v[140:141] op_sel_hi:[1,0]
	v_mul_f32_e32 v144, v144, v144
	v_pk_mul_f32 v[146:147], v[130:131], v[144:145] op_sel_hi:[1,0]
	v_exp_f32_e32 v136, v136
	v_exp_f32_e32 v140, v140
	v_exp_f32_e32 v137, v137
	v_exp_f32_e32 v141, v141
	v_exp_f32_e32 v138, v138
	v_exp_f32_e32 v142, v142
	v_exp_f32_e32 v139, v139
	v_exp_f32_e32 v143, v143
	v_pk_mul_f32 v[148:149], v[128:129], v[144:145] op_sel_hi:[1,0]
	v_pk_add_f32 v[128:129], v[136:137], 1.0 op_sel_hi:[1,0]
	v_pk_add_f32 v[130:131], v[138:139], 1.0 op_sel_hi:[1,0]
	v_pk_add_f32 v[134:135], v[142:143], 1.0 op_sel_hi:[1,0]
	v_pk_add_f32 v[132:133], v[140:141], 1.0 op_sel_hi:[1,0]
	v_pk_mul_f32 v[122:123], v[122:123], v[144:145] op_sel_hi:[1,0]
	v_pk_mul_f32 v[120:121], v[120:121], v[144:145] op_sel_hi:[1,0]
	v_rcp_f32_e32 v128, v128
	v_rcp_f32_e32 v132, v132
	v_rcp_f32_e32 v129, v129
	v_rcp_f32_e32 v133, v133
	v_rcp_f32_e32 v130, v130
	v_rcp_f32_e32 v134, v134
	v_rcp_f32_e32 v131, v131
	v_rcp_f32_e32 v135, v135
	s_nop 0
	v_pk_mul_f32 v[124:125], v[146:147], v[130:131]
	v_pk_mul_f32 v[126:127], v[148:149], v[128:129]
	v_pk_mul_f32 v[128:129], v[122:123], v[134:135]
	v_pk_mul_f32 v[122:123], v[120:121], v[132:133]
	v_cvt_pk_bf16_f32 v120, v126, v127
	v_cvt_pk_bf16_f32 v121, v124, v125
	v_cvt_pk_bf16_f32 v122, v122, v123
	v_cvt_pk_bf16_f32 v123, v128, v129
	v_lshl_add_u64 v[124:125], s[4:5], 0, v[82:83]
	global_store_dwordx4 v[124:125], v[120:123], off nt
	s_or_b32 s4, s33, 0x1000
	s_add_u32 s4, s20, s4
	s_waitcnt vmcnt(7)
	v_cvt_f32_u32_e32 v120, v163
	v_cvt_f32_u32_e32 v121, v162
	s_addc_u32 s5, s68, 0
	v_fmac_f32_e32 v121, 0x4f800000, v120
	v_fmamk_f32 v120, v121, 0x30000000, v234
	v_rsq_f32_e32 v128, v120
	s_nop 0
	v_mul_f32_e32 v124, 0xbfb8aa3b, v128
	v_pk_mul_f32 v[122:123], v[118:119], v[124:125] op_sel_hi:[1,0]
	v_pk_mul_f32 v[120:121], v[116:117], v[124:125] op_sel_hi:[1,0]
	v_pk_mul_f32 v[126:127], v[110:111], v[124:125] op_sel_hi:[1,0]
	v_pk_mul_f32 v[124:125], v[108:109], v[124:125] op_sel_hi:[1,0]
	v_mul_f32_e32 v128, v128, v128
	v_pk_mul_f32 v[130:131], v[114:115], v[128:129] op_sel_hi:[1,0]
	v_exp_f32_e32 v120, v120
	v_exp_f32_e32 v124, v124
	v_exp_f32_e32 v121, v121
	v_exp_f32_e32 v125, v125
	v_exp_f32_e32 v122, v122
	v_exp_f32_e32 v126, v126
	v_exp_f32_e32 v123, v123
	v_exp_f32_e32 v127, v127
	v_pk_mul_f32 v[132:133], v[112:113], v[128:129] op_sel_hi:[1,0]
	v_pk_add_f32 v[112:113], v[120:121], 1.0 op_sel_hi:[1,0]
	v_pk_add_f32 v[114:115], v[122:123], 1.0 op_sel_hi:[1,0]
	v_pk_add_f32 v[118:119], v[126:127], 1.0 op_sel_hi:[1,0]
	v_pk_add_f32 v[116:117], v[124:125], 1.0 op_sel_hi:[1,0]
	v_pk_mul_f32 v[106:107], v[106:107], v[128:129] op_sel_hi:[1,0]
	v_pk_mul_f32 v[104:105], v[104:105], v[128:129] op_sel_hi:[1,0]
	v_rcp_f32_e32 v112, v112
	v_rcp_f32_e32 v116, v116
	v_rcp_f32_e32 v113, v113
	v_rcp_f32_e32 v117, v117
	v_rcp_f32_e32 v114, v114
	v_rcp_f32_e32 v118, v118
	v_rcp_f32_e32 v115, v115
	v_rcp_f32_e32 v119, v119
	s_nop 0
	v_pk_mul_f32 v[108:109], v[130:131], v[114:115]
	v_pk_mul_f32 v[110:111], v[132:133], v[112:113]
	v_pk_mul_f32 v[112:113], v[106:107], v[118:119]
	v_pk_mul_f32 v[106:107], v[104:105], v[116:117]
	v_cvt_pk_bf16_f32 v104, v110, v111
	v_cvt_pk_bf16_f32 v105, v108, v109
	v_cvt_pk_bf16_f32 v106, v106, v107
	v_cvt_pk_bf16_f32 v107, v112, v113
	v_lshl_add_u64 v[108:109], s[4:5], 0, v[82:83]
	global_store_dwordx4 v[108:109], v[104:107], off nt
	s_or_b32 s4, s33, 0x1800
	s_add_u32 s4, s20, s4
	s_waitcnt vmcnt(7)
	v_cvt_f32_u32_e32 v104, v161
	v_cvt_f32_u32_e32 v105, v160
	s_addc_u32 s5, s68, 0
	v_fmac_f32_e32 v105, 0x4f800000, v104
	v_fmamk_f32 v104, v105, 0x30000000, v234
	v_rsq_f32_e32 v112, v104
	s_nop 0
	v_mul_f32_e32 v108, 0xbfb8aa3b, v112
	v_pk_mul_f32 v[106:107], v[78:79], v[108:109] op_sel_hi:[1,0]
	v_pk_mul_f32 v[104:105], v[76:77], v[108:109] op_sel_hi:[1,0]
	v_pk_mul_f32 v[110:111], v[70:71], v[108:109] op_sel_hi:[1,0]
	v_pk_mul_f32 v[108:109], v[68:69], v[108:109] op_sel_hi:[1,0]
	v_mul_f32_e32 v112, v112, v112
	v_pk_mul_f32 v[114:115], v[74:75], v[112:113] op_sel_hi:[1,0]
	v_exp_f32_e32 v104, v104
	v_exp_f32_e32 v108, v108
	v_exp_f32_e32 v105, v105
	v_exp_f32_e32 v109, v109
	v_exp_f32_e32 v106, v106
	v_exp_f32_e32 v110, v110
	v_exp_f32_e32 v107, v107
	v_exp_f32_e32 v111, v111
	v_pk_mul_f32 v[116:117], v[72:73], v[112:113] op_sel_hi:[1,0]
	v_pk_add_f32 v[72:73], v[104:105], 1.0 op_sel_hi:[1,0]
	v_pk_add_f32 v[74:75], v[106:107], 1.0 op_sel_hi:[1,0]
	v_pk_add_f32 v[78:79], v[110:111], 1.0 op_sel_hi:[1,0]
	v_pk_add_f32 v[76:77], v[108:109], 1.0 op_sel_hi:[1,0]
	v_pk_mul_f32 v[66:67], v[66:67], v[112:113] op_sel_hi:[1,0]
	v_pk_mul_f32 v[64:65], v[64:65], v[112:113] op_sel_hi:[1,0]
	v_rcp_f32_e32 v72, v72
	v_rcp_f32_e32 v76, v76
	v_rcp_f32_e32 v73, v73
	v_rcp_f32_e32 v77, v77
	v_rcp_f32_e32 v74, v74
	v_rcp_f32_e32 v78, v78
	v_rcp_f32_e32 v75, v75
	v_rcp_f32_e32 v79, v79
	s_nop 0
	v_pk_mul_f32 v[68:69], v[114:115], v[74:75]
	v_pk_mul_f32 v[70:71], v[116:117], v[72:73]
	v_pk_mul_f32 v[72:73], v[66:67], v[78:79]
	v_pk_mul_f32 v[66:67], v[64:65], v[76:77]
	v_cvt_pk_bf16_f32 v64, v70, v71
	v_cvt_pk_bf16_f32 v65, v68, v69
	v_cvt_pk_bf16_f32 v66, v66, v67
	v_cvt_pk_bf16_f32 v67, v72, v73
	v_lshl_add_u64 v[68:69], s[4:5], 0, v[82:83]
	global_store_dwordx4 v[68:69], v[64:67], off nt
	s_add_i32 s4, s33, 0x160000
	s_add_u32 s4, s20, s4
	s_waitcnt vmcnt(7)
	v_cvt_f32_u32_e32 v64, v159
	v_cvt_f32_u32_e32 v65, v158
	s_addc_u32 s5, s68, 0
	v_fmac_f32_e32 v65, 0x4f800000, v64
	v_fmamk_f32 v64, v65, 0x30000000, v234
	v_rsq_f32_e32 v72, v64
	s_nop 0
	v_mul_f32_e32 v68, 0xbfb8aa3b, v72
	v_pk_mul_f32 v[66:67], v[62:63], v[68:69] op_sel_hi:[1,0]
	v_pk_mul_f32 v[64:65], v[60:61], v[68:69] op_sel_hi:[1,0]
	v_pk_mul_f32 v[70:71], v[54:55], v[68:69] op_sel_hi:[1,0]
	v_pk_mul_f32 v[68:69], v[52:53], v[68:69] op_sel_hi:[1,0]
	v_mul_f32_e32 v72, v72, v72
	v_pk_mul_f32 v[74:75], v[58:59], v[72:73] op_sel_hi:[1,0]
	v_exp_f32_e32 v64, v64
	v_exp_f32_e32 v68, v68
	v_exp_f32_e32 v65, v65
	v_exp_f32_e32 v69, v69
	v_exp_f32_e32 v66, v66
	v_exp_f32_e32 v70, v70
	v_exp_f32_e32 v67, v67
	v_exp_f32_e32 v71, v71
	v_pk_mul_f32 v[76:77], v[56:57], v[72:73] op_sel_hi:[1,0]
	v_pk_add_f32 v[56:57], v[64:65], 1.0 op_sel_hi:[1,0]
	v_pk_add_f32 v[58:59], v[66:67], 1.0 op_sel_hi:[1,0]
	v_pk_add_f32 v[62:63], v[70:71], 1.0 op_sel_hi:[1,0]
	v_pk_add_f32 v[60:61], v[68:69], 1.0 op_sel_hi:[1,0]
	v_pk_mul_f32 v[50:51], v[50:51], v[72:73] op_sel_hi:[1,0]
	v_pk_mul_f32 v[48:49], v[48:49], v[72:73] op_sel_hi:[1,0]
	v_rcp_f32_e32 v56, v56
	v_rcp_f32_e32 v60, v60
	v_rcp_f32_e32 v57, v57
	v_rcp_f32_e32 v61, v61
	v_rcp_f32_e32 v58, v58
	v_rcp_f32_e32 v62, v62
	v_rcp_f32_e32 v59, v59
	v_rcp_f32_e32 v63, v63
	s_nop 0
	v_pk_mul_f32 v[52:53], v[74:75], v[58:59]
	v_pk_mul_f32 v[54:55], v[76:77], v[56:57]
	v_pk_mul_f32 v[56:57], v[50:51], v[62:63]
	v_pk_mul_f32 v[50:51], v[48:49], v[60:61]
	v_cvt_pk_bf16_f32 v48, v54, v55
	v_cvt_pk_bf16_f32 v49, v52, v53
	v_cvt_pk_bf16_f32 v50, v50, v51
	v_cvt_pk_bf16_f32 v51, v56, v57
	v_lshl_add_u64 v[52:53], s[4:5], 0, v[82:83]
	global_store_dwordx4 v[52:53], v[48:51], off nt
	s_add_i32 s4, s33, 0x160800
	s_add_u32 s4, s20, s4
	s_waitcnt vmcnt(7)
	v_cvt_f32_u32_e32 v48, v157
	v_cvt_f32_u32_e32 v49, v156
	s_addc_u32 s5, s68, 0
	v_fmac_f32_e32 v49, 0x4f800000, v48
	v_fmamk_f32 v48, v49, 0x30000000, v234
	v_rsq_f32_e32 v56, v48
	s_nop 0
	v_mul_f32_e32 v52, 0xbfb8aa3b, v56
	v_pk_mul_f32 v[50:51], v[46:47], v[52:53] op_sel_hi:[1,0]
	v_pk_mul_f32 v[48:49], v[44:45], v[52:53] op_sel_hi:[1,0]
	v_pk_mul_f32 v[54:55], v[38:39], v[52:53] op_sel_hi:[1,0]
	v_pk_mul_f32 v[52:53], v[36:37], v[52:53] op_sel_hi:[1,0]
	v_mul_f32_e32 v56, v56, v56
	v_pk_mul_f32 v[58:59], v[42:43], v[56:57] op_sel_hi:[1,0]
	v_exp_f32_e32 v48, v48
	v_exp_f32_e32 v52, v52
	v_exp_f32_e32 v49, v49
	v_exp_f32_e32 v53, v53
	v_exp_f32_e32 v50, v50
	v_exp_f32_e32 v54, v54
	v_exp_f32_e32 v51, v51
	v_exp_f32_e32 v55, v55
	v_pk_mul_f32 v[60:61], v[40:41], v[56:57] op_sel_hi:[1,0]
	v_pk_add_f32 v[40:41], v[48:49], 1.0 op_sel_hi:[1,0]
	v_pk_add_f32 v[42:43], v[50:51], 1.0 op_sel_hi:[1,0]
	v_pk_add_f32 v[46:47], v[54:55], 1.0 op_sel_hi:[1,0]
	v_pk_add_f32 v[44:45], v[52:53], 1.0 op_sel_hi:[1,0]
	v_pk_mul_f32 v[34:35], v[34:35], v[56:57] op_sel_hi:[1,0]
	v_pk_mul_f32 v[32:33], v[32:33], v[56:57] op_sel_hi:[1,0]
	v_rcp_f32_e32 v40, v40
	v_rcp_f32_e32 v44, v44
	v_rcp_f32_e32 v41, v41
	v_rcp_f32_e32 v45, v45
	v_rcp_f32_e32 v42, v42
	v_rcp_f32_e32 v46, v46
	v_rcp_f32_e32 v43, v43
	v_rcp_f32_e32 v47, v47
	s_nop 0
	v_pk_mul_f32 v[36:37], v[58:59], v[42:43]
	v_pk_mul_f32 v[38:39], v[60:61], v[40:41]
	v_pk_mul_f32 v[40:41], v[34:35], v[46:47]
	v_pk_mul_f32 v[34:35], v[32:33], v[44:45]
	v_cvt_pk_bf16_f32 v32, v38, v39
	v_cvt_pk_bf16_f32 v33, v36, v37
	v_cvt_pk_bf16_f32 v34, v34, v35
	v_cvt_pk_bf16_f32 v35, v40, v41
	v_lshl_add_u64 v[36:37], s[4:5], 0, v[82:83]
	global_store_dwordx4 v[36:37], v[32:35], off nt
	s_add_i32 s4, s33, 0x161000
	s_add_u32 s4, s20, s4
	s_waitcnt vmcnt(7)
	v_cvt_f32_u32_e32 v32, v155
	v_cvt_f32_u32_e32 v33, v154
	s_addc_u32 s5, s68, 0
	s_add_i32 s33, s33, 0x161800
	v_fmac_f32_e32 v33, 0x4f800000, v32
	v_fmamk_f32 v32, v33, 0x30000000, v234
	v_rsq_f32_e32 v40, v32
	s_nop 0
	v_mul_f32_e32 v36, 0xbfb8aa3b, v40
	v_pk_mul_f32 v[34:35], v[30:31], v[36:37] op_sel_hi:[1,0]
	v_pk_mul_f32 v[32:33], v[28:29], v[36:37] op_sel_hi:[1,0]
	v_pk_mul_f32 v[38:39], v[22:23], v[36:37] op_sel_hi:[1,0]
	v_pk_mul_f32 v[36:37], v[20:21], v[36:37] op_sel_hi:[1,0]
	v_mul_f32_e32 v40, v40, v40
	v_pk_mul_f32 v[42:43], v[26:27], v[40:41] op_sel_hi:[1,0]
	v_exp_f32_e32 v32, v32
	v_exp_f32_e32 v36, v36
	v_exp_f32_e32 v33, v33
	v_exp_f32_e32 v37, v37
	v_exp_f32_e32 v34, v34
	v_exp_f32_e32 v38, v38
	v_exp_f32_e32 v35, v35
	v_exp_f32_e32 v39, v39
	v_pk_mul_f32 v[44:45], v[24:25], v[40:41] op_sel_hi:[1,0]
	v_pk_add_f32 v[24:25], v[32:33], 1.0 op_sel_hi:[1,0]
	v_pk_add_f32 v[26:27], v[34:35], 1.0 op_sel_hi:[1,0]
	v_pk_add_f32 v[30:31], v[38:39], 1.0 op_sel_hi:[1,0]
	v_pk_add_f32 v[28:29], v[36:37], 1.0 op_sel_hi:[1,0]
	v_pk_mul_f32 v[18:19], v[18:19], v[40:41] op_sel_hi:[1,0]
	v_pk_mul_f32 v[16:17], v[16:17], v[40:41] op_sel_hi:[1,0]
	v_rcp_f32_e32 v24, v24
	v_rcp_f32_e32 v28, v28
	v_rcp_f32_e32 v25, v25
	v_rcp_f32_e32 v29, v29
	v_rcp_f32_e32 v26, v26
	v_rcp_f32_e32 v30, v30
	v_rcp_f32_e32 v27, v27
	v_rcp_f32_e32 v31, v31
	s_nop 0
	v_pk_mul_f32 v[20:21], v[42:43], v[26:27]
	v_pk_mul_f32 v[22:23], v[44:45], v[24:25]
	v_pk_mul_f32 v[24:25], v[18:19], v[30:31]
	v_pk_mul_f32 v[18:19], v[16:17], v[28:29]
	v_cvt_pk_bf16_f32 v16, v22, v23
	v_cvt_pk_bf16_f32 v17, v20, v21
	v_cvt_pk_bf16_f32 v18, v18, v19
	v_cvt_pk_bf16_f32 v19, v24, v25
	v_lshl_add_u64 v[20:21], s[4:5], 0, v[82:83]
	global_store_dwordx4 v[20:21], v[16:19], off nt
	s_add_u32 s4, s20, s33
	s_addc_u32 s5, s68, 0
	s_waitcnt vmcnt(7)
	v_cvt_f32_u32_e32 v16, v153
	v_cvt_f32_u32_e32 v17, v152
	s_andn2_b64 vcc, exec, s[38:39]
	v_fmac_f32_e32 v17, 0x4f800000, v16
	v_fmamk_f32 v16, v17, 0x30000000, v234
	v_rsq_f32_e32 v24, v16
	s_nop 0
	v_mul_f32_e32 v20, 0xbfb8aa3b, v24
	v_pk_mul_f32 v[18:19], v[14:15], v[20:21] op_sel_hi:[1,0]
	v_pk_mul_f32 v[16:17], v[12:13], v[20:21] op_sel_hi:[1,0]
	v_pk_mul_f32 v[22:23], v[6:7], v[20:21] op_sel_hi:[1,0]
	v_pk_mul_f32 v[20:21], v[4:5], v[20:21] op_sel_hi:[1,0]
	v_mul_f32_e32 v24, v24, v24
	v_pk_mul_f32 v[26:27], v[10:11], v[24:25] op_sel_hi:[1,0]
	v_exp_f32_e32 v16, v16
	v_exp_f32_e32 v20, v20
	v_exp_f32_e32 v17, v17
	v_exp_f32_e32 v21, v21
	v_exp_f32_e32 v18, v18
	v_exp_f32_e32 v22, v22
	v_exp_f32_e32 v19, v19
	v_exp_f32_e32 v23, v23
	v_pk_mul_f32 v[28:29], v[8:9], v[24:25] op_sel_hi:[1,0]
	v_pk_add_f32 v[8:9], v[16:17], 1.0 op_sel_hi:[1,0]
	v_pk_add_f32 v[10:11], v[18:19], 1.0 op_sel_hi:[1,0]
	v_pk_add_f32 v[14:15], v[22:23], 1.0 op_sel_hi:[1,0]
	v_pk_add_f32 v[12:13], v[20:21], 1.0 op_sel_hi:[1,0]
	v_pk_mul_f32 v[2:3], v[2:3], v[24:25] op_sel_hi:[1,0]
	v_pk_mul_f32 v[0:1], v[0:1], v[24:25] op_sel_hi:[1,0]
	v_rcp_f32_e32 v8, v8
	v_rcp_f32_e32 v12, v12
	v_rcp_f32_e32 v9, v9
	v_rcp_f32_e32 v13, v13
	v_rcp_f32_e32 v10, v10
	v_rcp_f32_e32 v14, v14
	v_rcp_f32_e32 v11, v11
	v_rcp_f32_e32 v15, v15
	s_nop 0
	v_pk_mul_f32 v[4:5], v[26:27], v[10:11]
	v_pk_mul_f32 v[6:7], v[28:29], v[8:9]
	v_pk_mul_f32 v[8:9], v[2:3], v[14:15]
	v_pk_mul_f32 v[2:3], v[0:1], v[12:13]
	v_cvt_pk_bf16_f32 v0, v6, v7
	v_cvt_pk_bf16_f32 v1, v4, v5
	v_cvt_pk_bf16_f32 v2, v2, v3
	v_cvt_pk_bf16_f32 v3, v8, v9
	v_lshl_add_u64 v[4:5], s[4:5], 0, v[82:83]
	s_mov_b64 s[4:5], -1
	global_store_dwordx4 v[4:5], v[0:3], off nt
	s_cbranch_vccnz .LBB0_791
	s_mov_b32 s101, 0
	s_andn2_b64 vcc, exec, s[0:1]
	s_cbranch_vccnz .LBB0_790
	s_mov_b32 s101, 1
	s_branch .LBB0_790

.LBB0_888:
	s_lshl_b32 s5, s5, 16
	s_lshl_b32 s6, s4, 20
	s_add_i32 s5, s6, s5
	s_add_u32 s72, s46, s5
	s_addc_u32 s73, s47, 0
	s_mov_b64 s[6:7], s[72:73]
	s_nop 0
	v_lshl_add_u64 v[128:129], s[6:7], 0, v[80:81]
	s_or_b32 s6, s5, 0x8000
	s_add_u32 s70, s46, s6
	s_addc_u32 s71, s47, 0
	s_mov_b64 s[6:7], s[70:71]
	s_add_u32 s68, s72, 0x800
	global_load_dwordx4 v[224:227], v[128:129], off
	s_addc_u32 s69, s73, 0
	v_lshl_add_u64 v[128:129], s[6:7], 0, v[80:81]
	s_mov_b64 s[6:7], s[68:69]
	global_load_dwordx4 v[228:231], v[128:129], off
	s_and_b64 vcc, exec, s[2:3]
	s_cbranch_vccz .Lab_p6
	s_barrier
.Lab_p6:
	s_waitcnt vmcnt(1)
	v_lshlrev_b32_e32 v208, 16, v224
	v_lshl_add_u64 v[128:129], s[6:7], 0, v[80:81]
	s_or_b32 s6, s5, 0x8800
	s_add_u32 s56, s46, s6
	s_addc_u32 s57, s47, 0
	s_mov_b64 s[6:7], s[56:57]
	global_load_dwordx4 v[204:207], v[128:129], off
	v_and_b32_e32 v209, 0xffff0000, v224
	v_lshl_add_u64 v[128:129], s[6:7], 0, v[80:81]
	s_or_b32 s6, s5, 0x1000
	s_add_u32 s48, s46, s6
	s_addc_u32 s49, s47, 0
	s_mov_b64 s[6:7], s[48:49]
	global_load_dwordx4 v[200:203], v[128:129], off
	v_lshlrev_b32_e32 v210, 16, v225
	v_lshl_add_u64 v[128:129], s[6:7], 0, v[80:81]
	s_or_b32 s6, s5, 0x9000
	s_add_u32 s44, s46, s6
	s_addc_u32 s45, s47, 0
	s_mov_b64 s[6:7], s[44:45]
	global_load_dwordx4 v[196:199], v[128:129], off
	v_and_b32_e32 v211, 0xffff0000, v225
	v_lshl_add_u64 v[128:129], s[6:7], 0, v[80:81]
	s_or_b32 s6, s5, 0x1800
	s_add_u32 s42, s46, s6
	s_addc_u32 s43, s47, 0
	s_mov_b64 s[6:7], s[42:43]
	global_load_dwordx4 v[192:195], v[128:129], off
	v_pk_add_f32 v[166:167], v[166:167], v[210:211]
	v_lshl_add_u64 v[128:129], s[6:7], 0, v[80:81]
	s_or_b32 s6, s5, 0x9800
	s_add_u32 s40, s46, s6
	s_addc_u32 s41, s47, 0
	s_mov_b64 s[6:7], s[40:41]
	global_load_dwordx4 v[188:191], v[128:129], off
	v_pk_add_f32 v[164:165], v[164:165], v[208:209]
	v_lshl_add_u64 v[128:129], s[6:7], 0, v[80:81]
	s_add_i32 s6, s5, 0x80000
	s_add_u32 s28, s46, s6
	s_addc_u32 s29, s47, 0
	s_mov_b64 s[6:7], s[28:29]
	global_load_dwordx4 v[184:187], v[128:129], off
	v_lshlrev_b32_e32 v208, 16, v226
	v_lshl_add_u64 v[128:129], s[6:7], 0, v[80:81]
	s_add_i32 s6, s5, 0x88000
	s_add_u32 s18, s46, s6
	s_addc_u32 s19, s47, 0
	s_mov_b64 s[6:7], s[18:19]
	global_load_dwordx4 v[180:183], v[128:129], off
	v_and_b32_e32 v209, 0xffff0000, v226
	v_lshl_add_u64 v[128:129], s[6:7], 0, v[80:81]
	s_add_i32 s6, s5, 0x80800
	s_add_u32 s16, s46, s6
	s_addc_u32 s17, s47, 0
	s_mov_b64 s[6:7], s[16:17]
	global_load_dwordx4 v[176:179], v[128:129], off
	v_lshlrev_b32_e32 v210, 16, v227
	v_lshl_add_u64 v[128:129], s[6:7], 0, v[80:81]
	s_add_i32 s6, s5, 0x88800
	s_add_u32 s14, s46, s6
	s_addc_u32 s15, s47, 0
	s_mov_b64 s[6:7], s[14:15]
	global_load_dwordx4 v[172:175], v[128:129], off
	v_and_b32_e32 v211, 0xffff0000, v227
	v_lshl_add_u64 v[128:129], s[6:7], 0, v[80:81]
	s_add_i32 s6, s5, 0x81000
	s_add_u32 s12, s46, s6
	s_addc_u32 s13, s47, 0
	s_mov_b64 s[6:7], s[12:13]
	global_load_dwordx4 v[168:171], v[128:129], off
	v_pk_add_f32 v[210:211], v[162:163], v[210:211]
	v_lshl_add_u64 v[128:129], s[6:7], 0, v[80:81]
	s_add_i32 s6, s5, 0x89000
	s_add_u32 s10, s46, s6
	s_addc_u32 s11, s47, 0
	s_mov_b64 s[6:7], s[10:11]
	global_load_dwordx4 v[156:159], v[128:129], off
	v_pk_add_f32 v[162:163], v[160:161], v[208:209]
	v_lshl_add_u64 v[128:129], s[6:7], 0, v[80:81]
	s_add_i32 s6, s5, 0x81800
	s_add_u32 s8, s46, s6
	s_addc_u32 s9, s47, 0
	s_mov_b64 s[6:7], s[8:9]
	global_load_dwordx4 v[152:155], v[128:129], off
	s_add_i32 s5, s5, 0x89800
	v_lshl_add_u64 v[128:129], s[6:7], 0, v[80:81]
	s_add_u32 s6, s46, s5
	s_addc_u32 s7, s47, 0
	s_mov_b64 s[80:81], s[6:7]
	global_load_dwordx4 v[140:143], v[128:129], off
	v_mul_f32_e32 v160, v165, v165
	v_lshl_add_u64 v[128:129], s[80:81], 0, v[80:81]
	global_load_dwordx4 v[128:131], v[128:129], off
	v_mul_f32_e32 v161, v167, v167
	v_fmac_f32_e32 v160, v164, v164
	v_fmac_f32_e32 v161, v166, v166
	v_add_f32_e32 v160, v160, v161
	v_mul_f32_e32 v161, v163, v163
	v_fmac_f32_e32 v161, v162, v162
	v_add_f32_e32 v160, v161, v160
	v_mul_f32_e32 v161, v211, v211
	v_fmac_f32_e32 v161, v210, v210
	v_add_f32_e32 v208, v161, v160
	v_cvt_pk_bf16_f32 v160, v164, v165
	v_cvt_pk_bf16_f32 v161, v166, v167
	v_cvt_pk_bf16_f32 v162, v162, v163
	v_cvt_pk_bf16_f32 v163, v210, v211
	s_ashr_i32 s5, s4, 31
	v_lshl_add_u64 v[164:165], s[72:73], 0, v[80:81]
	global_store_dwordx4 v[164:165], v[160:163], off
	s_lshl_b64 s[4:5], s[4:5], 11
	s_waitcnt vmcnt(15)
	v_lshlrev_b32_e32 v160, 16, v228
	v_and_b32_e32 v161, 0xffff0000, v228
	v_lshlrev_b32_e32 v162, 16, v229
	v_and_b32_e32 v163, 0xffff0000, v229
	v_pk_add_f32 v[150:151], v[150:151], v[162:163]
	v_pk_add_f32 v[148:149], v[148:149], v[160:161]
	v_lshlrev_b32_e32 v162, 16, v231
	v_and_b32_e32 v163, 0xffff0000, v231
	v_lshlrev_b32_e32 v160, 16, v230
	v_and_b32_e32 v161, 0xffff0000, v230
	v_pk_add_f32 v[164:165], v[146:147], v[162:163]
	v_mul_f32_e32 v146, v149, v149
	v_mul_f32_e32 v147, v151, v151
	v_pk_add_f32 v[144:145], v[144:145], v[160:161]
	v_fmac_f32_e32 v146, v148, v148
	v_fmac_f32_e32 v147, v150, v150
	v_add_f32_e32 v146, v146, v147
	v_mul_f32_e32 v147, v145, v145
	v_fmac_f32_e32 v147, v144, v144
	v_add_f32_e32 v146, v147, v146
	v_mul_f32_e32 v147, v165, v165
	v_fmac_f32_e32 v147, v164, v164
	v_add_f32_e32 v146, v147, v146
	v_and_b32_e32 v160, 64, v237
	v_add_f32_e32 v147, v208, v146
	v_xor_b32_e32 v146, 16, v237
	v_add_u32_e32 v166, 64, v160
	v_cmp_lt_i32_e32 vcc, v146, v166
	v_cvt_pk_bf16_f32 v162, v144, v145
	v_xor_b32_e32 v144, 32, v237
	v_cndmask_b32_e32 v146, v237, v146, vcc
	v_lshlrev_b32_e32 v146, 2, v146
	ds_bpermute_b32 v167, v146, v147
	v_cmp_lt_i32_e32 vcc, v144, v166
	v_cvt_pk_bf16_f32 v160, v148, v149
	v_cvt_pk_bf16_f32 v161, v150, v151
	v_cndmask_b32_e32 v144, v237, v144, vcc
	s_waitcnt lgkmcnt(0)
	v_add_f32_e32 v148, v147, v167
	v_lshlrev_b32_e32 v147, 2, v144
	ds_bpermute_b32 v149, v147, v148
	v_cvt_pk_bf16_f32 v163, v164, v165
	v_lshl_add_u64 v[144:145], s[70:71], 0, v[80:81]
	global_store_dwordx4 v[144:145], v[160:163], off
	v_lshl_add_u64 v[144:145], v[82:83], 0, s[4:5]
	s_and_saveexec_b64 s[4:5], s[36:37]
	s_movk_i32 s72, 0xffe0
	s_cbranch_execz .LBB0_890
	s_waitcnt lgkmcnt(0)
	v_add_f32_e32 v148, v148, v149
	v_cvt_f64_f32_e32 v[148:149], v148
	v_ldexp_f64 v[148:149], v[148:149], 20
	v_trunc_f64_e32 v[148:149], v[148:149]
	v_ldexp_f64 v[150:151], v[148:149], s72
	v_floor_f64_e32 v[150:151], v[150:151]
	v_fmac_f64_e32 v[148:149], 0xc1f00000, v[150:151]
	v_cvt_u32_f64_e32 v148, v[148:149]
	v_cvt_i32_f64_e32 v149, v[150:151]
	global_atomic_add_x2 v[144:145], v[148:149], off
